# grid barriers: no L1 invalidates (the only buffer re-read after a rewrite, z at ws+0, is read with sc1 loads / sc1 LDS-DMA in phases 4 and 5; every other buffer is loaded for the first time in the lau
# speedup vs baseline: 1.0711x; 1.0187x over previous
; DI float bflo(unsigned u) { return __uint_as_float(u << 16); }
; DI float bfhi(unsigned u) { return __uint_as_float(u & 0xffff0000u); }
; DI void phase_rwkv_out(const Params& p, char* lds) {
;     ...
;         const int t = 16 * tg + i16; const int row = row0 + t;
;         u16* z = (u16*)(p.ws + W_XB) + (size_t)row * DM + 512 + h * 64;
;         const u16* qt = QT + (size_t)u * 4096 + t * 64 + 8 * g; const bf16x8 bq0 = *(const bf16x8*)qt, bq1 = *(const bf16x8*)(qt + 32);
;         { const float a_ = p.mix[1024 + h * 64 + lane], b_ = p.gn_g[h * 64 + lane], c_ = p.gn_b[h * 64 + lane];
;             asm volatile("s_waitcnt lgkmcnt(0)" ::: "memory"); pw[lane] = a_; pw[64 + lane] = b_; pw[128 + lane] = c_; asm volatile("s_waitcnt lgkmcnt(0)" ::: "memory"); }
;         const int wofs = 16 * (g & 1) + 8 * (g >> 1);
;         const int mode = t > 0 ? 0 : (prm ? (c > 0 ? 0 : 1) : 2);
;         uint2 ylw[4], cvw[4], grw[4], pvw[4];
;         { const u16* pr_ = proj + (size_t)row * NC + h * 64 + wofs; const u16* pp_ = proj + (size_t)(mode == 0 ? row - 1 : row) * NC + C_RV + h * 64 + wofs;
; #pragma unroll
;             for (int mp = 0; mp < 2; ++mp) {
;                 unwiden16(*(const uint4*)(z + 32 * mp + wofs), ylw[2 * mp], ylw[2 * mp + 1]);
;                 unwiden16(*(const uint4*)(pr_ + C_RV + 32 * mp), cvw[2 * mp], cvw[2 * mp + 1]);
;                 unwiden16(*(const uint4*)(pr_ + C_GR + 32 * mp), grw[2 * mp], grw[2 * mp + 1]);
;                 unwiden16(*(const uint4*)(pp_ + 32 * mp), pvw[2 * mp], pvw[2 * mp + 1]); } }
;         f32x4 y[4];
; #pragma unroll
;         for (int mt = 0; mt < 4; ++mt) {
;             const uint2 yl = ylw[mt]; f32x4 a = {bflo(yl.x), bfhi(yl.x), bflo(yl.y), bfhi(yl.y)};
;             const u16* sp = SST + (size_t)u * 4096 + (16 * mt + i16) * 64 + 8 * g;
;             a = __builtin_amdgcn_mfma_f32_16x16x32_bf16(*(const bf16x8*)sp, bq0, a, 0, 0, 0); a = __builtin_amdgcn_mfma_f32_16x16x32_bf16(*(const bf16x8*)(sp + 32), bq1, a, 0, 0, 0);
;             y[mt] = a;
.LBB0_495:
	v_cmp_lt_i32_e32 vcc, s21, v1
	s_and_saveexec_b64 s[0:1], vcc
	s_xor_b64 s[0:1], exec, s[0:1]
	v_add_u32_e32 v2, 0xffffe000, v1
	v_lshrrev_b32_e32 v36, 3, v2
	v_add_u32_e32 v18, 0xffffe800, v1
	v_lshl_add_u32 v2, v36, 4, v107
	s_or_saveexec_b64 s[0:1], s[0:1]
	v_mov_b32_e32 v4, 0
	v_mov_b32_e32 v3, 2
	v_mov_b32_e32 v5, v1
	s_xor_b64 exec, exec, s[0:1]
	v_ashrrev_i32_e32 v18, 2, v1
	v_ashrrev_i32_e32 v36, 12, v1
	v_and_b32_e32 v3, 0x7f, v18
	v_lshlrev_b32_e32 v2, 13, v36
	v_cmp_eq_u32_e32 vcc, 0, v3
	v_lshrrev_b32_e32 v5, 9, v1
	v_lshl_or_b32 v2, v3, 6, v2
	v_and_b32_e32 v4, 48, v105
	v_cndmask_b32_e64 v3, 0, 1, vcc
	s_or_b64 exec, exec, s[0:1]
	v_lshlrev_b32_e32 v5, 6, v5
	v_and_b32_e32 v81, 0x1c0, v5
	v_or_b32_e32 v5, v81, v218
	v_lshlrev_b32_e32 v6, 2, v5
	v_mov_b32_e32 v7, v221
	v_lshl_add_u64 v[8:9], s[78:79], 0, v[6:7]
	v_add_co_u32_e32 v8, vcc, s22, v8
	v_or_b32_e32 v37, v4, v223
	s_nop 0
	v_addc_co_u32_e32 v9, vcc, 0, v9, vcc
	global_load_dword v172, v6, s[46:47]
	global_load_dword v173, v6, s[48:49]
	global_load_dword v174, v[8:9], off
	v_ashrrev_i32_e32 v19, 31, v18
	v_cmp_eq_u32_e32 vcc, 0, v37
	v_add_u32_e32 v2, v37, v2
	v_lshlrev_b64 v[38:39], 13, v[18:19]
	v_cndmask_b32_e32 v119, 0, v3, vcc
	v_mov_b32_e32 v5, v221
	v_lshlrev_b32_e32 v4, 7, v37
	v_lshlrev_b32_e32 v220, 1, v81
	v_lshl_add_u64 v[6:7], s[6:7], 0, v[38:39]
	v_mad_i64_i32 v[8:9], s[0:1], v2, s18, v[74:75]
	v_cmp_eq_u32_e32 vcc, 0, v119
	v_lshl_add_u64 v[4:5], v[6:7], 0, v[4:5]
	v_lshl_add_u64 v[6:7], v[8:9], 0, v[220:221]
	v_subbrev_co_u32_e32 v13, vcc, 0, v2, vcc
	v_ashrrev_i32_e32 v3, 31, v2
	v_mad_i64_i32 v[8:9], s[0:1], v13, s18, v[74:75]
	v_lshl_add_u64 v[6:7], v[6:7], 0, v[76:77]
	v_lshlrev_b64 v[2:3], 11, v[2:3]
	v_lshl_add_u64 v[8:9], v[8:9], 0, v[220:221]
	v_add_co_u32_e32 v34, vcc, s22, v6
	v_lshl_add_u64 v[2:3], s[54:55], 0, v[2:3]
	v_lshl_add_u64 v[4:5], v[4:5], 0, v[72:73]
	v_lshl_add_u64 v[32:33], v[8:9], 0, v[76:77]
	v_addc_co_u32_e32 v35, vcc, 0, v7, vcc
	v_lshl_add_u64 v[84:85], v[2:3], 0, v[220:221]
	global_load_dwordx4 v[28:31], v[4:5], off
	global_load_dwordx4 v[24:27], v[4:5], off offset:64
	s_waitcnt lgkmcnt(0)
	v_add_co_u32_e32 v50, vcc, s22, v32
	v_lshl_add_u64 v[48:49], v[84:85], 0, v[76:77]
	s_nop 0
	v_addc_co_u32_e32 v51, vcc, 0, v33, vcc
	v_lshl_add_u64 v[32:33], v[32:33], 0, s[10:11]
	v_lshl_add_u64 v[38:39], v[70:71], 0, v[38:39]
	v_add_co_u32_e32 v68, vcc, s22, v38
	v_lshlrev_b64 v[18:19], 8, v[18:19]
	s_nop 0
	v_addc_co_u32_e32 v69, vcc, 0, v39, vcc
	v_lshl_add_u64 v[18:19], s[8:9], 0, v[18:19]
	v_lshlrev_b32_e32 v220, 2, v37
	v_lshl_add_u64 v[18:19], v[18:19], 0, v[220:221]
	v_cmp_ne_u32_e32 vcc, 0, v119
	v_cmp_ne_u32_e64 s[0:1], 1, v119
	global_load_dwordx4 v[40:43], v[48:49], off offset:1024 sc1
	global_load_dwordx4 v[2:5], v[34:35], off offset:2048
	global_load_dwordx4 v[6:9], v[34:35], off offset:3328
	global_load_dwordx4 v[20:23], v[50:51], off offset:2048
	global_load_dwordx4 v[44:47], v[48:49], off offset:1088 sc1
	global_load_dwordx4 v[10:13], v[34:35], off offset:2112
	global_load_dwordx4 v[14:17], v[34:35], off offset:3392
	global_load_dwordx4 v[32:35], v[32:33], off offset:64
	s_nop 0
	global_load_dwordx4 v[48:51], v[38:39], off
	global_load_dwordx4 v[52:55], v[38:39], off offset:2048
	global_load_dwordx4 v[56:59], v[68:69], off
	global_load_dwordx4 v[60:63], v[68:69], off offset:2048
	global_load_dwordx4 v[64:67], v[38:39], off offset:64
	global_load_dwordx4 v[88:91], v[38:39], off offset:2112
	global_load_dwordx4 v[92:95], v[68:69], off offset:64
	global_load_dwordx4 v[96:99], v[68:69], off offset:2112
	global_load_dword v86, v[18:19], off
	s_waitcnt vmcnt(20)
	ds_write_b32 v87, v173 offset:512
	s_waitcnt vmcnt(19)
	ds_write2st64_b32 v87, v174, v172 offset1:1
	s_waitcnt lgkmcnt(0)
	s_waitcnt vmcnt(16)
	v_mov_b32_e32 v37, v42
	s_nop 1
	v_permlane16_swap_b32_e32 v40, v37
	v_permlane16_swap_b32_e32 v41, v43
	s_waitcnt vmcnt(15)
	v_mov_b32_e32 v112, v4
	v_mov_b32_e32 v111, v5
	s_waitcnt vmcnt(12)
	v_mov_b32_e32 v4, v46
	v_mov_b32_e32 v5, v47
	s_waitcnt vmcnt(10)
	v_mov_b32_e32 v108, v16
	v_mov_b32_e32 v83, v17
	v_lshlrev_b32_e32 v16, 16, v40
	v_and_b32_e32 v17, 0xffff0000, v40
	v_lshlrev_b32_e32 v18, 16, v41
	v_and_b32_e32 v19, 0xffff0000, v41
	v_permlane16_swap_b32_e32 v44, v4
	v_permlane16_swap_b32_e32 v45, v5
	v_lshlrev_b32_e32 v40, 16, v37
	v_and_b32_e32 v41, 0xffff0000, v37
	v_lshlrev_b32_e32 v42, 16, v43
	s_waitcnt vmcnt(8)
	v_mfma_f32_16x16x32_bf16 v[16:19], v[48:51], v[28:31], v[16:19]
	v_and_b32_e32 v43, 0xffff0000, v43
	v_lshlrev_b32_e32 v46, 16, v44
	v_and_b32_e32 v47, 0xffff0000, v44
	s_waitcnt vmcnt(7)
; DI float bflo(unsigned u) { return __uint_as_float(u << 16); }
; DI float bfhi(unsigned u) { return __uint_as_float(u & 0xffff0000u); }
; DI float xadd16(float v) { const unsigned x = __float_as_uint(v); auto r = __builtin_amdgcn_permlane16_swap(x, x, false, false); return __uint_as_float(r[0]) + __uint_as_float(r[1]); }
; DI float xadd32(float v) { const unsigned x = __float_as_uint(v); auto r = __builtin_amdgcn_permlane32_swap(x, x, false, false); return __uint_as_float(r[0]) + __uint_as_float(r[1]); }
; DI void phase_rwkv_out(const Params& p, char* lds) {
;     ...
;         f32x4 y[4];
; #pragma unroll
;         for (int mt = 0; mt < 4; ++mt) {
;             const uint2 yl = ylw[mt]; f32x4 a = {bflo(yl.x), bfhi(yl.x), bflo(yl.y), bfhi(yl.y)};
;             const u16* sp = SST + (size_t)u * 4096 + (16 * mt + i16) * 64 + 8 * g;
;             a = __builtin_amdgcn_mfma_f32_16x16x32_bf16(*(const bf16x8*)sp, bq0, a, 0, 0, 0); a = __builtin_amdgcn_mfma_f32_16x16x32_bf16(*(const bf16x8*)(sp + 32), bq1, a, 0, 0, 0);
;             y[mt] = a;
;         }
;         float s1 = 0.f;
; #pragma unroll
;         for (int mt = 0; mt < 4; ++mt) s1 += (y[mt][0] + y[mt][1]) + (y[mt][2] + y[mt][3]);
;         s1 = xadd16(s1); s1 = xadd32(s1);
;         const float mu = s1 * (1.f / 64.f); float s2 = 0.f;
; #pragma unroll
;         for (int mt = 0; mt < 4; ++mt)
; #pragma unroll
;             for (int e = 0; e < 4; ++e) { const float d = y[mt][e] - mu; s2 += d * d; }
;         s2 = xadd16(s2); s2 = xadd32(s2);
;         const float rs = __builtin_amdgcn_rsqf(s2 * (1.f / 64.f) + 64e-5f);
;         const float bon = bonus[(size_t)u * 64 + t];
;         uint2 wz[4];
; #pragma unroll
;         for (int mt = 0; mt < 4; ++mt) {
;             const int i0 = 16 * mt + 4 * g; const int hj = h * 64 + i0;
;             const uint2 cvp = cvw[mt]; const float cv[4] = {bflo(cvp.x), bfhi(cvp.x), bflo(cvp.y), bfhi(cvp.y)};
;             float pv[4];
;             if (mode == 0) { const uint2 w = pvw[mt]; pv[0] = bflo(w.x); pv[1] = bfhi(w.x); pv[2] = bflo(w.y); pv[3] = bfhi(w.y); }
;             else if (mode == 1) { pv[0] = pv[1] = pv[2] = pv[3] = 0.f; }
;             else { const float4 w = *(const float4*)(p.st_shift + (size_t)b * 1664 + 1024 + hj); pv[0] = w.x; pv[1] = w.y; pv[2] = w.z; pv[3] = w.w; }
	v_mfma_f32_16x16x32_bf16 v[40:43], v[52:55], v[28:31], v[40:43]
	v_lshlrev_b32_e32 v48, 16, v45
	v_and_b32_e32 v49, 0xffff0000, v45
	v_lshlrev_b32_e32 v44, 16, v4
	v_and_b32_e32 v45, 0xffff0000, v4
	s_waitcnt vmcnt(6)
	v_mfma_f32_16x16x32_bf16 v[48:51], v[56:59], v[28:31], v[46:49]
	v_mov_b32_e32 v38, v22
	v_mov_b32_e32 v39, v23
	v_mov_b32_e32 v110, v8
	v_lshlrev_b32_e32 v46, 16, v5
	v_and_b32_e32 v47, 0xffff0000, v5
	s_waitcnt vmcnt(4)
	v_mfma_f32_16x16x32_bf16 v[16:19], v[64:67], v[24:27], v[16:19]
	v_mov_b32_e32 v109, v9
	v_mov_b32_e32 v114, v12
	v_mov_b32_e32 v113, v13
	v_mfma_f32_16x16x32_bf16 v[28:31], v[60:63], v[28:31], v[44:47]
	v_mov_b32_e32 v115, v34
	s_nop 2
	v_add_f32_e32 v4, v16, v17
	v_add_f32_e32 v5, v18, v19
	s_waitcnt vmcnt(3)
	v_mfma_f32_16x16x32_bf16 v[40:43], v[88:91], v[24:27], v[40:43]
	v_add_f32_e32 v4, v4, v5
	v_add_f32_e32 v4, 0, v4
	v_mov_b32_e32 v116, v35
	s_waitcnt vmcnt(2)
	v_mfma_f32_16x16x32_bf16 v[44:47], v[92:95], v[24:27], v[48:51]
	v_permlane16_swap_b32_e32 v2, v112
	s_nop 1
	v_add_f32_e32 v8, v40, v41
	s_waitcnt vmcnt(1)
	v_mfma_f32_16x16x32_bf16 v[22:25], v[96:99], v[24:27], v[28:31]
	v_add_f32_e32 v9, v42, v43
	s_nop 0
	v_add_f32_e32 v12, v44, v45
	v_add_f32_e32 v13, v46, v47
	v_add_f32_e32 v5, v8, v9
	v_add_f32_e32 v8, v12, v13
	s_nop 1
	v_add_f32_e32 v26, v22, v23
	v_add_f32_e32 v27, v24, v25
	v_add_f32_e32 v4, v4, v5
	v_add_f32_e32 v9, v26, v27
	v_add_f32_e32 v4, v4, v8
	v_add_f32_e32 v4, v4, v9
	v_mov_b32_e32 v5, v4
	s_nop 1
	v_permlane16_swap_b32_e32 v4, v5
	v_add_f32_e32 v4, v4, v5
	v_mov_b32_e32 v5, v4
	s_nop 1
	v_permlane32_swap_b32_e32 v4, v5
	v_add_f32_e32 v4, v4, v5
	v_mul_f32_e32 v8, 0x3c800000, v4
	v_pk_add_f32 v[90:91], v[16:17], v[8:9] op_sel_hi:[1,0] neg_lo:[0,1] neg_hi:[0,1]
	v_pk_add_f32 v[88:89], v[18:19], v[8:9] op_sel_hi:[1,0] neg_lo:[0,1] neg_hi:[0,1]
	v_mul_f32_e32 v16, v91, v91
	v_pk_fma_f32 v[16:17], v[90:91], v[90:91], v[16:17] op_sel_hi:[1,1,0]
	v_mul_f32_e32 v18, v89, v89
	v_pk_fma_f32 v[16:17], v[88:89], v[88:89], v[16:17]
	v_pk_add_f32 v[94:95], v[40:41], v[8:9] op_sel_hi:[1,0] neg_lo:[0,1] neg_hi:[0,1]
	v_pk_add_f32 v[16:17], v[18:19], v[16:17] op_sel_hi:[0,1]
	v_pk_add_f32 v[12:13], v[22:23], v[8:9] op_sel_hi:[1,0] neg_lo:[0,1] neg_hi:[0,1]
	v_mul_f32_e32 v22, v95, v95
	v_pk_fma_f32 v[16:17], v[94:95], v[94:95], v[16:17]
	v_pk_add_f32 v[92:93], v[42:43], v[8:9] op_sel_hi:[1,0] neg_lo:[0,1] neg_hi:[0,1]
	v_pk_add_f32 v[16:17], v[22:23], v[16:17] op_sel_hi:[0,1]
	v_pk_add_f32 v[96:97], v[44:45], v[8:9] op_sel_hi:[1,0] neg_lo:[0,1] neg_hi:[0,1]
	v_pk_add_f32 v[4:5], v[46:47], v[8:9] op_sel_hi:[1,0] neg_lo:[0,1] neg_hi:[0,1]
	v_pk_add_f32 v[8:9], v[24:25], v[8:9] op_sel_hi:[1,0] neg_lo:[0,1] neg_hi:[0,1]
	v_mul_f32_e32 v24, v93, v93
	v_pk_fma_f32 v[16:17], v[92:93], v[92:93], v[16:17]
	v_mul_f32_e32 v26, v97, v97
	v_pk_add_f32 v[16:17], v[24:25], v[16:17] op_sel_hi:[0,1]
	v_pk_fma_f32 v[16:17], v[96:97], v[96:97], v[16:17]
	v_mul_f32_e32 v28, v5, v5
	v_pk_add_f32 v[16:17], v[26:27], v[16:17] op_sel_hi:[0,1]
	v_pk_fma_f32 v[16:17], v[4:5], v[4:5], v[16:17]
	v_mul_f32_e32 v30, v13, v13
	v_pk_add_f32 v[16:17], v[28:29], v[16:17] op_sel_hi:[0,1]
	v_pk_fma_f32 v[16:17], v[12:13], v[12:13], v[16:17]
	v_mul_f32_e32 v18, v9, v9
	v_pk_add_f32 v[16:17], v[30:31], v[16:17] op_sel_hi:[0,1]
	v_pk_fma_f32 v[16:17], v[8:9], v[8:9], v[16:17]
	v_permlane16_swap_b32_e32 v3, v111
	v_pk_add_f32 v[16:17], v[18:19], v[16:17] op_sel_hi:[0,1]
	v_mov_b32_e32 v17, v16
	s_nop 1
	v_permlane16_swap_b32_e32 v16, v17
	v_add_f32_e32 v117, v16, v17
	v_mov_b32_e32 v118, v117
	v_mad_i64_i32 v[16:17], s[14:15], v36, s23, v[78:79]
	v_permlane16_swap_b32_e32 v6, v110
	v_permlane16_swap_b32_e32 v7, v109
	v_permlane16_swap_b32_e32 v20, v38
	v_permlane16_swap_b32_e32 v21, v39
	v_permlane16_swap_b32_e32 v10, v114
	v_permlane16_swap_b32_e32 v11, v113
	v_permlane16_swap_b32_e32 v14, v108
	v_permlane16_swap_b32_e32 v15, v83
	v_permlane16_swap_b32_e32 v32, v115
	v_permlane16_swap_b32_e32 v33, v116
	v_permlane32_swap_b32_e32 v117, v118
	v_lshl_add_u64 v[98:99], v[16:17], 0, s[12:13]
	s_and_saveexec_b64 s[14:15], vcc
	s_xor_b64 s[14:15], exec, s[14:15]
	s_cbranch_execz .LBB0_503
	v_mov_b32_e32 v19, 0
	v_mov_b32_e32 v18, 0
	v_mov_b32_e32 v17, 0
	v_mov_b32_e32 v16, 0
	s_and_saveexec_b64 s[16:17], s[0:1]
	s_cbranch_execz .LBB0_502
	v_or_b32_e32 v16, v81, v100
	v_lshlrev_b32_e32 v220, 2, v16
	v_lshl_add_u64 v[16:17], v[98:99], 0, v[220:221]
	global_load_dwordx4 v[16:19], v[16:17], off

; DI unsigned xb_ld(unsigned* p) { return __hip_atomic_load(p, __ATOMIC_RELAXED, __HIP_MEMORY_SCOPE_AGENT); }
; #define XB_SPIN(cond, bar) do { unsigned _sp = 0; while (cond) { __builtin_amdgcn_s_sleep(2); \
;     if ((++_sp & 255u) == 0u) { if (xb_ld(&(bar)[XB_TMO])) break; if (_sp > XB_SPIN_CAP) { atomicAdd(&(bar)[XB_TMO], 1u); break; } } } } while (0)
; DI void xcd_barrier(const XcdBarrier& b) {
;     ...
;             XB_SPIN(xb_ld(&bar[XB_XGEN(b.x)]) == gen, bar);
;             __builtin_amdgcn_fence(__ATOMIC_ACQUIRE, "agent");
;             asm volatile("s_waitcnt vmcnt(0)" ::: "memory");
.LBB0_554:
	s_or_b64 exec, exec, s[6:7]
	s_waitcnt vmcnt(0)
	s_waitcnt vmcnt(0)

; DI unsigned xb_add(unsigned* p, unsigned v) { return __hip_atomic_fetch_add(p, v, __ATOMIC_RELAXED, __HIP_MEMORY_SCOPE_AGENT); }
; DI void xcd_barrier(const XcdBarrier& b) {
;     ...
;             __builtin_amdgcn_fence(__ATOMIC_ACQUIRE, "agent");
;             xb_add(&bar[XB_XGEN(b.x)], 1u);
.LBB0_572:
	s_or_b64 exec, exec, s[4:5]
	s_mov_b64 s[4:5], exec
	v_mbcnt_lo_u32_b32 v1, s4, 0
	v_mbcnt_hi_u32_b32 v1, s5, v1
	v_cmp_eq_u32_e32 vcc, 0, v1
	s_waitcnt vmcnt(0)
	s_and_saveexec_b64 s[6:7], vcc
	s_cbranch_execz .LBB0_574
	s_bcnt1_i32_b64 s4, s[4:5]
	v_mov_b32_e32 v1, 0x2000
	v_mov_b32_e32 v2, s4
	global_atomic_add v1, v2, s[2:3] offset:1024

; DI float4 ntld4(const float* p) { const f32x4 v = __builtin_nontemporal_load((const f32x4*)p); return (float4){v[0], v[1], v[2], v[3]}; }
; DI void gemm_out(const Params& p, char* lds) {
;     ...
;     for (int tile = vb; tile < ntile; tile += gridDim.x) {
;         int tid = threadIdx.x; asm volatile("" : "+v"(tid));
;         const int lane = tid & 63, wave = __builtin_amdgcn_readfirstlane(tid >> 6); const int wn = wave >> 1, wm = wave & 1; const int q = lane & 15, g = lane >> 4;
;         const int mt = tile >> 3, nt = tile & 7; const int m0 = mt * 96, n0 = nt * 128;
;         f32x4 acc[4][3];
; #pragma unroll
;         for (int a = 0; a < 4; ++a)
; #pragma unroll
;             for (int b = 0; b < 3; ++b) acc[a][b] = (f32x4){0.f, 0.f, 0.f, 0.f};
;         unsigned soffb[4], soffa[3];
; #pragma unroll
;         for (int i = 0; i < 4; ++i) { const int row = 8 * (i * 4 + wave) + (lane >> 3); const int ch = (lane & 7) ^ ((row >> 1) & 7); soffb[i] = (unsigned)(row * 1024 + ch * 8); }
; #pragma unroll
;         for (int i = 0; i < 3; ++i) { const int row = 8 * (i * 4 + wave) + (lane >> 3); const int ch = (lane & 7) ^ ((row >> 1) & 7); soffa[i] = (unsigned)(row * 1024 + ch * 8); }
;         const u16* ga = A + (size_t)m0 * 1024; const u16* gb = B + (size_t)n0 * 1024;
;     ...
;         OSTAGE(0, 0);
;         float4 xres[3][4];
; #pragma unroll
;         for (int tt = 0; tt < 3; ++tt) { const int row = m0 + wm * 48 + tt * 16 + q; const float* xr = row < NTP ? p.x_p + (size_t)row * DM : p.x_s + (size_t)(row - NTP) * DM;
; #pragma unroll
;             for (int ct = 0; ct < 4; ++ct) xres[tt][ct] = ntld4(xr + n0 + wn * 64 + ct * 16 + 4 * g); }
;         __syncthreads();
;         for (int kt = 0; kt < 16; ++kt) {
;             if (kt + 1 < 16) OSTAGE((kt + 1) & 1, kt + 1);
;             const char* sb = lds + (kt & 1) * 28672; const char* sa = sb + 16384;
.LBB0_575:
	s_or_b64 exec, exec, s[0:1]
	s_cmpk_gt_i32 s64, 0x57f
	s_waitcnt lgkmcnt(0)
	s_barrier
	s_cmpk_gt_i32 s64, 0x41f
	s_cbranch_scc1 .LBB0_578
	s_mov_b32 s33, s64
	v_readlane_b32 s95, v236, 8
	s_add_u32 s10, s54, 0x2940000
	s_addc_u32 s11, s55, 0
	v_writelane_b32 v236, s10, 9
	s_nop 1
	v_writelane_b32 v236, s11, 11
	s_lshr_b32 s82, s33, 3
	s_lshl_b32 s82, s82, 7
	s_and_b32 s0, s33, 7
	s_lshl_b32 s0, s0, 7
	v_mov_b32_e32 v75, 0
	v_readfirstlane_b32 s4, v0
	s_lshr_b32 s6, s4, 6
	v_bfe_u32 v2, v0, 3, 3
	s_ashr_i32 s83, s82, 31
	v_lshl_or_b32 v2, s6, 3, v2
	s_lshl_b64 s[4:5], s[82:83], 11
	v_lshrrev_b32_e32 v3, 1, v2
	s_add_u32 s4, s54, s4
	v_xor_b32_e32 v3, v3, v0
	s_addc_u32 s5, s55, s5
	s_ashr_i32 s1, s0, 31
	s_lshl_b32 s8, s6, 10
	s_lshl_b64 s[6:7], s[0:1], 11
	v_lshlrev_b32_e32 v3, 4, v3
	s_add_u32 s6, s10, s6
	v_and_b32_e32 v3, 0x70, v3
	v_add_u32_e32 v4, 32, v2
	s_addc_u32 s7, s11, s7
	v_lshl_or_b32 v74, v2, 11, v3
	s_add_i32 s1, s8, 0
	v_lshrrev_b32_e32 v5, 1, v4
	v_add_u32_e32 v6, 64, v2
	v_add_u32_e32 v8, 0x60, v2
	v_lshl_add_u64 v[2:3], s[4:5], 0, v[74:75]
	s_mov_b32 m0, s1
	v_xor_b32_e32 v5, v5, v0
	global_load_lds_dwordx4 v[2:3], off sc1
	v_lshl_add_u64 v[2:3], s[6:7], 0, v[74:75]
	s_add_i32 m0, s1, 0x4000
	v_lshrrev_b32_e32 v7, 1, v6
	global_load_lds_dwordx4 v[2:3], off
	v_lshlrev_b32_e32 v2, 4, v5
	v_and_b32_e32 v2, 0x70, v2
	v_lshl_or_b32 v74, v4, 11, v2
	v_lshl_add_u64 v[2:3], s[4:5], 0, v[74:75]
	s_add_i32 m0, s1, 0x1000
	v_xor_b32_e32 v7, v7, v0
	global_load_lds_dwordx4 v[2:3], off sc1
	v_lshl_add_u64 v[2:3], s[6:7], 0, v[74:75]
	s_add_i32 m0, s1, 0x5000
	v_lshrrev_b32_e32 v9, 1, v8
	global_load_lds_dwordx4 v[2:3], off
	v_lshlrev_b32_e32 v2, 4, v7
	v_and_b32_e32 v2, 0x70, v2
	v_lshl_or_b32 v74, v6, 11, v2
	v_lshl_add_u64 v[2:3], s[4:5], 0, v[74:75]
	s_add_i32 m0, s1, 0x2000
	v_xor_b32_e32 v9, v9, v0
	global_load_lds_dwordx4 v[2:3], off sc1
	v_lshl_add_u64 v[2:3], s[6:7], 0, v[74:75]
	s_add_i32 m0, s1, 0x6000
	global_load_lds_dwordx4 v[2:3], off
	v_lshlrev_b32_e32 v2, 4, v9
	v_and_b32_e32 v2, 0x70, v2
	v_lshl_or_b32 v74, v8, 11, v2
	v_lshl_add_u64 v[2:3], s[4:5], 0, v[74:75]
	s_add_i32 m0, s1, 0x3000
	global_load_lds_dwordx4 v[2:3], off sc1
	v_lshl_add_u64 v[2:3], s[6:7], 0, v[74:75]
	s_add_i32 m0, s1, 0x7000
	global_load_lds_dwordx4 v[2:3], off
	s_mov_b32 s5, 0
	s_mov_b64 s[8:9], 0x80
	s_mov_b64 s[10:11], 0x100
	s_mov_b64 s[12:13], 0x180
	s_mov_b64 s[14:15], 0x200
	s_mov_b64 s[16:17], 0x280
	s_mov_b64 s[18:19], 0x300
	s_mov_b64 s[20:21], 0x380
	s_mov_b64 s[22:23], 0x400
	s_mov_b64 s[24:25], 0x480
	s_mov_b64 s[26:27], 0x500
	s_mov_b64 s[28:29], 0x580
	s_mov_b64 s[30:31], 0x600
	s_mov_b64 s[36:37], 0x680
	s_mov_b64 s[68:69], 0x700
	s_mov_b64 s[70:71], 0x780
	s_waitcnt vmcnt(0)
.Lo_tile:
	v_mov_b32_e32 v18, v0
	s_ashr_i32 s83, s82, 31
	v_readfirstlane_b32 s1, v18
	s_ashr_i32 s7, s1, 6
	s_ashr_i32 s4, s1, 7
	s_and_b32 s6, s7, 1
	v_bfe_u32 v2, v18, 3, 3
	s_lshl_b64 s[38:39], s[82:83], 11
	v_lshl_or_b32 v2, s7, 3, v2
	s_add_u32 s38, s54, s38
	v_lshrrev_b32_e32 v3, 1, v2
	s_addc_u32 s39, s55, s39
	s_ashr_i32 s1, s0, 31
	v_xor_b32_e32 v3, v3, v18
	s_lshl_b64 s[50:51], s[0:1], 11
	v_readlane_b32 s1, v236, 9
	v_lshlrev_b32_e32 v2, 10, v2
	v_lshlrev_b32_e32 v3, 3, v3
	s_add_u32 s50, s1, s50
	v_readlane_b32 s1, v236, 11
	v_and_or_b32 v74, v3, 56, v2
	s_addc_u32 s51, s1, s51
	s_lshl_b32 s1, s7, 10
	v_lshlrev_b64 v[66:67], 1, v[74:75]
	s_add_i32 s1, s1, 0
	v_add_u32_e32 v2, 0x8000, v74
	v_bfe_u32 v93, v18, 5, 1
	v_lshrrev_b32_e32 v8, 1, v18
	v_mov_b32_e32 v3, v75
	v_lshl_add_u64 v[76:77], s[38:39], 0, v[66:67]
	s_add_i32 s86, s1, 0x8000
	v_bitop3_b32 v10, v93, v8, 7 bitop3:0x78
	v_lshl_add_u64 v[8:9], v[76:77], 0, s[8:9]
	s_mov_b32 m0, s86
	v_lshl_add_u64 v[78:79], s[50:51], 0, v[66:67]
	s_add_i32 s87, s1, 0xc000
	v_lshlrev_b64 v[68:69], 1, v[2:3]
	v_add_u32_e32 v4, 0x10000, v74
	s_waitcnt vmcnt(0) lgkmcnt(0)
	s_barrier
	v_mov_b32_e32 v5, v75
	global_load_lds_dwordx4 v[8:9], off sc1
	v_lshl_add_u64 v[8:9], v[78:79], 0, s[8:9]
	s_mov_b32 m0, s87
	v_lshl_add_u64 v[80:81], s[38:39], 0, v[68:69]
	s_add_i32 s88, s1, 0x9000
	global_load_lds_dwordx4 v[8:9], off
	v_lshl_add_u64 v[2:3], v[80:81], 0, s[8:9]
	s_mov_b32 m0, s88
	v_lshl_add_u64 v[82:83], s[50:51], 0, v[68:69]
	s_add_i32 s89, s1, 0xd000
	v_lshlrev_b64 v[70:71], 1, v[4:5]
	v_add_u32_e32 v6, 0x18000, v74
	v_mov_b32_e32 v7, v75
	global_load_lds_dwordx4 v[2:3], off sc1
	v_lshl_add_u64 v[2:3], v[82:83], 0, s[8:9]
	s_mov_b32 m0, s89
	v_lshl_add_u64 v[84:85], s[38:39], 0, v[70:71]
	s_add_i32 s91, s1, 0xa000
	global_load_lds_dwordx4 v[2:3], off
	v_lshl_add_u64 v[2:3], v[84:85], 0, s[8:9]
	s_mov_b32 m0, s91
	v_lshl_add_u64 v[86:87], s[50:51], 0, v[70:71]
	s_add_i32 s92, s1, 0xe000
	v_lshlrev_b64 v[72:73], 1, v[6:7]
	global_load_lds_dwordx4 v[2:3], off sc1
	v_lshl_add_u64 v[2:3], v[86:87], 0, s[8:9]
	s_mov_b32 m0, s92
	v_lshl_add_u64 v[88:89], s[38:39], 0, v[72:73]
	s_add_i32 s93, s1, 0xb000
	v_and_b32_e32 v94, 31, v18
	global_load_lds_dwordx4 v[2:3], off
	v_lshl_add_u64 v[2:3], v[88:89], 0, s[8:9]
	s_mov_b32 m0, s93
	v_lshl_add_u64 v[90:91], s[50:51], 0, v[72:73]
	s_add_i32 s94, s1, 0xf000
	s_lshl_b32 s7, s4, 13
	v_lshlrev_b32_e32 v116, 7, v94
	global_load_lds_dwordx4 v[2:3], off sc1
	v_lshl_add_u64 v[2:3], v[90:91], 0, s[8:9]
	s_mov_b32 m0, s94
	v_lshl_add_u32 v6, v10, 4, 0
	global_load_lds_dwordx4 v[2:3], off
	v_add3_u32 v74, v6, s7, v116
	ds_read_b128 v[2:5], v74 offset:16384
	s_lshl_b32 s38, s6, 13
	v_add3_u32 v96, v6, s38, v116
	v_bfe_u32 v117, v18, 1, 3
	ds_read_b128 v[6:9], v96
	ds_read_b128 v[10:13], v96 offset:4096
	ds_read_b128 v[14:17], v74 offset:20480
	v_bitop3_b32 v18, v93, v117, 2 bitop3:0x36
	v_lshl_add_u32 v18, v18, 4, 0
	v_add3_u32 v95, v18, s7, v116
	ds_read_b128 v[50:53], v95 offset:16384
	s_waitcnt lgkmcnt(0)
; DI void gemm_out(const Params& p, char* lds) {
;     ...
;         for (int kt = 0; kt < 16; ++kt) {
;             if (kt + 1 < 16) OSTAGE((kt + 1) & 1, kt + 1);
;             const char* sb = lds + (kt & 1) * 28672; const char* sa = sb + 16384;
; #pragma unroll
;             for (int ks = 0; ks < 2; ++ks) {
;                 bf16x8 fw[4], fx[3];
; #pragma unroll
;                 for (int ct = 0; ct < 4; ++ct) fw[ct] = *(const bf16x8*)(sb + swz(wn * 64 + ct * 16 + q, 4 * ks + g));
; #pragma unroll
;                 for (int tt = 0; tt < 3; ++tt) fx[tt] = *(const bf16x8*)(sa + swz(wm * 48 + tt * 16 + q, 4 * ks + g));
; #pragma unroll
;                 for (int ct = 0; ct < 4; ++ct)
; #pragma unroll
;                     for (int tt = 0; tt < 3; ++tt) acc[ct][tt] = __builtin_amdgcn_mfma_f32_16x16x32_bf16(fw[ct], fx[tt], acc[ct][tt], 0, 0, 0);
;             }
;             __syncthreads();
	v_mfma_f32_32x32x16_bf16 v[34:49], v[6:9], v[2:5], 0
	v_add3_u32 v97, v18, s38, v116
	ds_read_b128 v[98:101], v97
	ds_read_b128 v[102:105], v97 offset:4096
	ds_read_b128 v[106:109], v95 offset:20480
	s_mov_b32 m0, s1
	s_add_i32 s39, s1, 0x5000
	s_add_i32 s50, s1, 0x2000
	s_add_i32 s51, s1, 0x6000
	s_add_i32 s83, s1, 0x3000
	v_mfma_f32_32x32x16_bf16 v[18:33], v[10:13], v[2:5], 0
	s_add_i32 s90, s1, 0x7000
	s_add_i32 s33, s33, s95
	s_waitcnt lgkmcnt(0)
	v_mfma_f32_32x32x16_bf16 v[34:49], v[98:101], v[50:53], v[34:49]
	v_mfma_f32_32x32x16_bf16 v[18:33], v[102:105], v[50:53], v[18:33]
	v_mfma_f32_32x32x16_bf16 v[50:65], v[6:9], v[14:17], 0
	v_mfma_f32_32x32x16_bf16 v[2:17], v[10:13], v[14:17], 0
	v_mfma_f32_32x32x16_bf16 v[50:65], v[98:101], v[106:109], v[50:65]
	v_bitop3_b32 v98, v93, v117, 4 bitop3:0x36
	v_lshl_add_u32 v99, v98, 4, 0
	v_add3_u32 v98, v99, s7, v116
	v_add3_u32 v99, v99, s38, v116
	v_mfma_f32_32x32x16_bf16 v[2:17], v[102:105], v[106:109], v[2:17]
	ds_read_b128 v[100:103], v98 offset:16384
	ds_read_b128 v[104:107], v99
	ds_read_b128 v[108:111], v99 offset:4096
	ds_read_b128 v[112:115], v98 offset:20480
	s_waitcnt lgkmcnt(0)
	v_mfma_f32_32x32x16_bf16 v[34:49], v[104:107], v[100:103], v[34:49]
	v_mfma_f32_32x32x16_bf16 v[18:33], v[108:111], v[100:103], v[18:33]
	v_bitop3_b32 v100, v93, v117, 6 bitop3:0x36
	v_lshl_add_u32 v101, v100, 4, 0
	v_add3_u32 v100, v101, s7, v116
	v_add3_u32 v101, v101, s38, v116
	s_add_i32 s7, s1, 0x4000
	s_add_i32 s38, s1, 0x1000
	s_cmpk_gt_i32 s33, 0x3ff
	v_mfma_f32_32x32x16_bf16 v[50:65], v[104:107], v[112:115], v[50:65]
	v_mfma_f32_32x32x16_bf16 v[2:17], v[108:111], v[112:115], v[2:17]
	ds_read_b128 v[238:241], v100 offset:16384
	ds_read_b128 v[242:245], v101
	ds_read_b128 v[246:249], v101 offset:4096
	ds_read_b128 v[250:253], v100 offset:20480
	s_waitcnt vmcnt(0) lgkmcnt(0)
	s_barrier
	ds_read_b128 v[102:105], v74 offset:49152
	ds_read_b128 v[106:109], v96 offset:32768
	ds_read_b128 v[110:113], v96 offset:36864
	ds_read_b128 v[114:117], v74 offset:53248
	v_mfma_f32_32x32x16_bf16 v[34:49], v[242:245], v[238:241], v[34:49]
	v_mfma_f32_32x32x16_bf16 v[18:33], v[246:249], v[238:241], v[18:33]
	v_lshl_add_u64 v[254:255], v[76:77], 0, s[10:11]
	global_load_lds_dwordx4 v[254:255], off sc1
	v_lshl_add_u64 v[254:255], v[78:79], 0, s[10:11]
	s_mov_b32 m0, s7
	s_nop 0
	global_load_lds_dwordx4 v[254:255], off
	v_mfma_f32_32x32x16_bf16 v[50:65], v[242:245], v[250:253], v[50:65]
	v_lshl_add_u64 v[254:255], v[80:81], 0, s[10:11]
	s_mov_b32 m0, s38
	s_nop 0
	global_load_lds_dwordx4 v[254:255], off sc1
	v_mfma_f32_32x32x16_bf16 v[2:17], v[246:249], v[250:253], v[2:17]
	s_waitcnt lgkmcnt(0)
	ds_read_b128 v[238:241], v95 offset:49152
	ds_read_b128 v[242:245], v97 offset:32768
	ds_read_b128 v[246:249], v97 offset:36864
	ds_read_b128 v[250:253], v95 offset:53248
	v_mfma_f32_32x32x16_bf16 v[34:49], v[106:109], v[102:105], v[34:49]
	v_lshl_add_u64 v[254:255], v[82:83], 0, s[10:11]
	s_mov_b32 m0, s39
	s_nop 0
	global_load_lds_dwordx4 v[254:255], off
	v_mfma_f32_32x32x16_bf16 v[18:33], v[110:113], v[102:105], v[18:33]
	v_lshl_add_u64 v[254:255], v[84:85], 0, s[10:11]
	s_mov_b32 m0, s50
	s_nop 0
	global_load_lds_dwordx4 v[254:255], off sc1
	v_mfma_f32_32x32x16_bf16 v[50:65], v[106:109], v[114:117], v[50:65]
	v_mfma_f32_32x32x16_bf16 v[2:17], v[110:113], v[114:117], v[2:17]
	s_waitcnt lgkmcnt(0)
	ds_read_b128 v[102:105], v98 offset:49152
	ds_read_b128 v[106:109], v99 offset:32768
	ds_read_b128 v[110:113], v99 offset:36864
	ds_read_b128 v[114:117], v98 offset:53248
	v_mfma_f32_32x32x16_bf16 v[34:49], v[242:245], v[238:241], v[34:49]
	v_lshl_add_u64 v[254:255], v[86:87], 0, s[10:11]
	s_mov_b32 m0, s51
	s_nop 0
	global_load_lds_dwordx4 v[254:255], off
	v_mfma_f32_32x32x16_bf16 v[18:33], v[246:249], v[238:241], v[18:33]
	v_lshl_add_u64 v[254:255], v[88:89], 0, s[10:11]
	s_mov_b32 m0, s83
	s_nop 0
	global_load_lds_dwordx4 v[254:255], off sc1
	v_mfma_f32_32x32x16_bf16 v[50:65], v[242:245], v[250:253], v[50:65]
	v_mfma_f32_32x32x16_bf16 v[2:17], v[246:249], v[250:253], v[2:17]
	s_waitcnt lgkmcnt(0)
	ds_read_b128 v[238:241], v100 offset:49152
	ds_read_b128 v[242:245], v101 offset:32768
	ds_read_b128 v[246:249], v101 offset:36864
	ds_read_b128 v[250:253], v100 offset:53248
	v_mfma_f32_32x32x16_bf16 v[34:49], v[106:109], v[102:105], v[34:49]
	v_lshl_add_u64 v[254:255], v[90:91], 0, s[10:11]
	s_mov_b32 m0, s90
	s_nop 0
	global_load_lds_dwordx4 v[254:255], off
	v_mfma_f32_32x32x16_bf16 v[18:33], v[110:113], v[102:105], v[18:33]
	v_mfma_f32_32x32x16_bf16 v[50:65], v[106:109], v[114:117], v[50:65]
	v_mfma_f32_32x32x16_bf16 v[2:17], v[110:113], v[114:117], v[2:17]
	s_mov_b32 m0, s86
	s_waitcnt vmcnt(0) lgkmcnt(0)
	s_barrier
; DI void gemm_out(const Params& p, char* lds) {
;     ...
;         for (int kt = 0; kt < 16; ++kt) {
;             if (kt + 1 < 16) OSTAGE((kt + 1) & 1, kt + 1);
;             const char* sb = lds + (kt & 1) * 28672; const char* sa = sb + 16384;
; #pragma unroll
;             for (int ks = 0; ks < 2; ++ks) {
;                 bf16x8 fw[4], fx[3];
; #pragma unroll
;                 for (int ct = 0; ct < 4; ++ct) fw[ct] = *(const bf16x8*)(sb + swz(wn * 64 + ct * 16 + q, 4 * ks + g));
; #pragma unroll
;                 for (int tt = 0; tt < 3; ++tt) fx[tt] = *(const bf16x8*)(sa + swz(wm * 48 + tt * 16 + q, 4 * ks + g));
; #pragma unroll
;                 for (int ct = 0; ct < 4; ++ct)
; #pragma unroll
;                     for (int tt = 0; tt < 3; ++tt) acc[ct][tt] = __builtin_amdgcn_mfma_f32_16x16x32_bf16(fw[ct], fx[tt], acc[ct][tt], 0, 0, 0);
;             }
;             __syncthreads();
	ds_read_b128 v[102:105], v74 offset:16384
	ds_read_b128 v[106:109], v96
	ds_read_b128 v[110:113], v96 offset:4096
	ds_read_b128 v[114:117], v74 offset:20480
	v_mfma_f32_32x32x16_bf16 v[34:49], v[242:245], v[238:241], v[34:49]
	v_mfma_f32_32x32x16_bf16 v[18:33], v[246:249], v[238:241], v[18:33]
	v_lshl_add_u64 v[254:255], v[76:77], 0, s[12:13]
	global_load_lds_dwordx4 v[254:255], off sc1
	v_lshl_add_u64 v[254:255], v[78:79], 0, s[12:13]
	s_mov_b32 m0, s87
	s_nop 0
	global_load_lds_dwordx4 v[254:255], off
	v_mfma_f32_32x32x16_bf16 v[50:65], v[242:245], v[250:253], v[50:65]
	v_lshl_add_u64 v[254:255], v[80:81], 0, s[12:13]
	s_mov_b32 m0, s88
	s_nop 0
	global_load_lds_dwordx4 v[254:255], off sc1
	v_mfma_f32_32x32x16_bf16 v[2:17], v[246:249], v[250:253], v[2:17]
	s_waitcnt lgkmcnt(0)
	ds_read_b128 v[238:241], v95 offset:16384
	ds_read_b128 v[242:245], v97
	ds_read_b128 v[246:249], v97 offset:4096
	ds_read_b128 v[250:253], v95 offset:20480
	v_mfma_f32_32x32x16_bf16 v[34:49], v[106:109], v[102:105], v[34:49]
	v_lshl_add_u64 v[254:255], v[82:83], 0, s[12:13]
	s_mov_b32 m0, s89
	s_nop 0
	global_load_lds_dwordx4 v[254:255], off
	v_mfma_f32_32x32x16_bf16 v[18:33], v[110:113], v[102:105], v[18:33]
	v_lshl_add_u64 v[254:255], v[84:85], 0, s[12:13]
	s_mov_b32 m0, s91
	s_nop 0
	global_load_lds_dwordx4 v[254:255], off sc1
	v_mfma_f32_32x32x16_bf16 v[50:65], v[106:109], v[114:117], v[50:65]
	v_mfma_f32_32x32x16_bf16 v[2:17], v[110:113], v[114:117], v[2:17]
	s_waitcnt lgkmcnt(0)
	ds_read_b128 v[102:105], v98 offset:16384
	ds_read_b128 v[106:109], v99
	ds_read_b128 v[110:113], v99 offset:4096
	ds_read_b128 v[114:117], v98 offset:20480
	v_mfma_f32_32x32x16_bf16 v[34:49], v[242:245], v[238:241], v[34:49]
	v_lshl_add_u64 v[254:255], v[86:87], 0, s[12:13]
	s_mov_b32 m0, s92
	s_nop 0
	global_load_lds_dwordx4 v[254:255], off
	v_mfma_f32_32x32x16_bf16 v[18:33], v[246:249], v[238:241], v[18:33]
	v_lshl_add_u64 v[254:255], v[88:89], 0, s[12:13]
	s_mov_b32 m0, s93
	s_nop 0
	global_load_lds_dwordx4 v[254:255], off sc1
	v_mfma_f32_32x32x16_bf16 v[50:65], v[242:245], v[250:253], v[50:65]
	v_mfma_f32_32x32x16_bf16 v[2:17], v[246:249], v[250:253], v[2:17]
	s_waitcnt lgkmcnt(0)
	ds_read_b128 v[238:241], v100 offset:16384
	ds_read_b128 v[242:245], v101
	ds_read_b128 v[246:249], v101 offset:4096
	ds_read_b128 v[250:253], v100 offset:20480
	v_mfma_f32_32x32x16_bf16 v[34:49], v[106:109], v[102:105], v[34:49]
	v_lshl_add_u64 v[254:255], v[90:91], 0, s[12:13]
	s_mov_b32 m0, s94
	s_nop 0
	global_load_lds_dwordx4 v[254:255], off
	v_mfma_f32_32x32x16_bf16 v[18:33], v[110:113], v[102:105], v[18:33]
	v_mfma_f32_32x32x16_bf16 v[50:65], v[106:109], v[114:117], v[50:65]
	v_mfma_f32_32x32x16_bf16 v[2:17], v[110:113], v[114:117], v[2:17]
	s_mov_b32 m0, s1
	s_waitcnt vmcnt(0) lgkmcnt(0)
	s_barrier
	ds_read_b128 v[102:105], v74 offset:49152
	ds_read_b128 v[106:109], v96 offset:32768
	ds_read_b128 v[110:113], v96 offset:36864
	ds_read_b128 v[114:117], v74 offset:53248
	v_mfma_f32_32x32x16_bf16 v[34:49], v[242:245], v[238:241], v[34:49]
	v_mfma_f32_32x32x16_bf16 v[18:33], v[246:249], v[238:241], v[18:33]
	v_lshl_add_u64 v[254:255], v[76:77], 0, s[14:15]
	global_load_lds_dwordx4 v[254:255], off sc1
	v_lshl_add_u64 v[254:255], v[78:79], 0, s[14:15]
	s_mov_b32 m0, s7
	s_nop 0
	global_load_lds_dwordx4 v[254:255], off
	v_mfma_f32_32x32x16_bf16 v[50:65], v[242:245], v[250:253], v[50:65]
	v_lshl_add_u64 v[254:255], v[80:81], 0, s[14:15]
	s_mov_b32 m0, s38
	s_nop 0
	global_load_lds_dwordx4 v[254:255], off sc1
	v_mfma_f32_32x32x16_bf16 v[2:17], v[246:249], v[250:253], v[2:17]
	s_waitcnt lgkmcnt(0)
	ds_read_b128 v[238:241], v95 offset:49152
	ds_read_b128 v[242:245], v97 offset:32768
	ds_read_b128 v[246:249], v97 offset:36864
	ds_read_b128 v[250:253], v95 offset:53248
	v_mfma_f32_32x32x16_bf16 v[34:49], v[106:109], v[102:105], v[34:49]
	v_lshl_add_u64 v[254:255], v[82:83], 0, s[14:15]
	s_mov_b32 m0, s39
	s_nop 0
	global_load_lds_dwordx4 v[254:255], off
	v_mfma_f32_32x32x16_bf16 v[18:33], v[110:113], v[102:105], v[18:33]
	v_lshl_add_u64 v[254:255], v[84:85], 0, s[14:15]
	s_mov_b32 m0, s50
	s_nop 0
	global_load_lds_dwordx4 v[254:255], off sc1
	v_mfma_f32_32x32x16_bf16 v[50:65], v[106:109], v[114:117], v[50:65]
	v_mfma_f32_32x32x16_bf16 v[2:17], v[110:113], v[114:117], v[2:17]
	s_waitcnt lgkmcnt(0)
	ds_read_b128 v[102:105], v98 offset:49152
	ds_read_b128 v[106:109], v99 offset:32768
	ds_read_b128 v[110:113], v99 offset:36864
	ds_read_b128 v[114:117], v98 offset:53248
	v_mfma_f32_32x32x16_bf16 v[34:49], v[242:245], v[238:241], v[34:49]
	v_lshl_add_u64 v[254:255], v[86:87], 0, s[14:15]
	s_mov_b32 m0, s51
	s_nop 0
	global_load_lds_dwordx4 v[254:255], off
	v_mfma_f32_32x32x16_bf16 v[18:33], v[246:249], v[238:241], v[18:33]
	v_lshl_add_u64 v[254:255], v[88:89], 0, s[14:15]
	s_mov_b32 m0, s83
	s_nop 0
	global_load_lds_dwordx4 v[254:255], off sc1
	v_mfma_f32_32x32x16_bf16 v[50:65], v[242:245], v[250:253], v[50:65]
	v_mfma_f32_32x32x16_bf16 v[2:17], v[246:249], v[250:253], v[2:17]
	s_waitcnt lgkmcnt(0)
	ds_read_b128 v[238:241], v100 offset:49152
	ds_read_b128 v[242:245], v101 offset:32768
	ds_read_b128 v[246:249], v101 offset:36864
	ds_read_b128 v[250:253], v100 offset:53248
	v_mfma_f32_32x32x16_bf16 v[34:49], v[106:109], v[102:105], v[34:49]
	v_lshl_add_u64 v[254:255], v[90:91], 0, s[14:15]
	s_mov_b32 m0, s90
	s_nop 0
	global_load_lds_dwordx4 v[254:255], off
	v_mfma_f32_32x32x16_bf16 v[18:33], v[110:113], v[102:105], v[18:33]
	v_mfma_f32_32x32x16_bf16 v[50:65], v[106:109], v[114:117], v[50:65]
	v_mfma_f32_32x32x16_bf16 v[2:17], v[110:113], v[114:117], v[2:17]
	s_mov_b32 m0, s86
	s_waitcnt vmcnt(0) lgkmcnt(0)
	s_barrier
; DI void gemm_out(const Params& p, char* lds) {
;     ...
;         for (int kt = 0; kt < 16; ++kt) {
;             if (kt + 1 < 16) OSTAGE((kt + 1) & 1, kt + 1);
;             const char* sb = lds + (kt & 1) * 28672; const char* sa = sb + 16384;
; #pragma unroll
;             for (int ks = 0; ks < 2; ++ks) {
;                 bf16x8 fw[4], fx[3];
; #pragma unroll
;                 for (int ct = 0; ct < 4; ++ct) fw[ct] = *(const bf16x8*)(sb + swz(wn * 64 + ct * 16 + q, 4 * ks + g));
; #pragma unroll
;                 for (int tt = 0; tt < 3; ++tt) fx[tt] = *(const bf16x8*)(sa + swz(wm * 48 + tt * 16 + q, 4 * ks + g));
; #pragma unroll
;                 for (int ct = 0; ct < 4; ++ct)
; #pragma unroll
;                     for (int tt = 0; tt < 3; ++tt) acc[ct][tt] = __builtin_amdgcn_mfma_f32_16x16x32_bf16(fw[ct], fx[tt], acc[ct][tt], 0, 0, 0);
;             }
;             __syncthreads();
;         }
	ds_read_b128 v[102:105], v74 offset:16384
	ds_read_b128 v[106:109], v96
	ds_read_b128 v[110:113], v96 offset:4096
	ds_read_b128 v[114:117], v74 offset:20480
	v_mfma_f32_32x32x16_bf16 v[34:49], v[242:245], v[238:241], v[34:49]
	v_mfma_f32_32x32x16_bf16 v[18:33], v[246:249], v[238:241], v[18:33]
	v_lshl_add_u64 v[254:255], v[76:77], 0, s[16:17]
	global_load_lds_dwordx4 v[254:255], off sc1
	v_lshl_add_u64 v[254:255], v[78:79], 0, s[16:17]
	s_mov_b32 m0, s87
	s_nop 0
	global_load_lds_dwordx4 v[254:255], off
	v_mfma_f32_32x32x16_bf16 v[50:65], v[242:245], v[250:253], v[50:65]
	v_lshl_add_u64 v[254:255], v[80:81], 0, s[16:17]
	s_mov_b32 m0, s88
	s_nop 0
	global_load_lds_dwordx4 v[254:255], off sc1
	v_mfma_f32_32x32x16_bf16 v[2:17], v[246:249], v[250:253], v[2:17]
	s_waitcnt lgkmcnt(0)
	ds_read_b128 v[238:241], v95 offset:16384
	ds_read_b128 v[242:245], v97
	ds_read_b128 v[246:249], v97 offset:4096
	ds_read_b128 v[250:253], v95 offset:20480
	v_mfma_f32_32x32x16_bf16 v[34:49], v[106:109], v[102:105], v[34:49]
	v_lshl_add_u64 v[254:255], v[82:83], 0, s[16:17]
	s_mov_b32 m0, s89
	s_nop 0
	global_load_lds_dwordx4 v[254:255], off
	v_mfma_f32_32x32x16_bf16 v[18:33], v[110:113], v[102:105], v[18:33]
	v_lshl_add_u64 v[254:255], v[84:85], 0, s[16:17]
	s_mov_b32 m0, s91
	s_nop 0
	global_load_lds_dwordx4 v[254:255], off sc1
	v_mfma_f32_32x32x16_bf16 v[50:65], v[106:109], v[114:117], v[50:65]
	v_mfma_f32_32x32x16_bf16 v[2:17], v[110:113], v[114:117], v[2:17]
	s_waitcnt lgkmcnt(0)
	ds_read_b128 v[102:105], v98 offset:16384
	ds_read_b128 v[106:109], v99
	ds_read_b128 v[110:113], v99 offset:4096
	ds_read_b128 v[114:117], v98 offset:20480
	v_mfma_f32_32x32x16_bf16 v[34:49], v[242:245], v[238:241], v[34:49]
	v_lshl_add_u64 v[254:255], v[86:87], 0, s[16:17]
	s_mov_b32 m0, s92
	s_nop 0
	global_load_lds_dwordx4 v[254:255], off
	v_mfma_f32_32x32x16_bf16 v[18:33], v[246:249], v[238:241], v[18:33]
	v_lshl_add_u64 v[254:255], v[88:89], 0, s[16:17]
	s_mov_b32 m0, s93
	s_nop 0
	global_load_lds_dwordx4 v[254:255], off sc1
	v_mfma_f32_32x32x16_bf16 v[50:65], v[242:245], v[250:253], v[50:65]
	v_mfma_f32_32x32x16_bf16 v[2:17], v[246:249], v[250:253], v[2:17]
	s_waitcnt lgkmcnt(0)
	ds_read_b128 v[238:241], v100 offset:16384
	ds_read_b128 v[242:245], v101
	ds_read_b128 v[246:249], v101 offset:4096
	ds_read_b128 v[250:253], v100 offset:20480
	v_mfma_f32_32x32x16_bf16 v[34:49], v[106:109], v[102:105], v[34:49]
	v_lshl_add_u64 v[254:255], v[90:91], 0, s[16:17]
	s_mov_b32 m0, s94
	s_nop 0
	global_load_lds_dwordx4 v[254:255], off
	v_mfma_f32_32x32x16_bf16 v[18:33], v[110:113], v[102:105], v[18:33]
	v_mfma_f32_32x32x16_bf16 v[50:65], v[106:109], v[114:117], v[50:65]
	v_mfma_f32_32x32x16_bf16 v[2:17], v[110:113], v[114:117], v[2:17]
	s_mov_b32 m0, s1
	s_waitcnt vmcnt(0) lgkmcnt(0)
	s_barrier
	ds_read_b128 v[102:105], v74 offset:49152
	ds_read_b128 v[106:109], v96 offset:32768
	ds_read_b128 v[110:113], v96 offset:36864
	ds_read_b128 v[114:117], v74 offset:53248
	v_mfma_f32_32x32x16_bf16 v[34:49], v[242:245], v[238:241], v[34:49]
	v_mfma_f32_32x32x16_bf16 v[18:33], v[246:249], v[238:241], v[18:33]
	v_lshl_add_u64 v[254:255], v[76:77], 0, s[18:19]
	global_load_lds_dwordx4 v[254:255], off sc1
	v_lshl_add_u64 v[254:255], v[78:79], 0, s[18:19]
	s_mov_b32 m0, s7
	s_nop 0
	global_load_lds_dwordx4 v[254:255], off
	v_mfma_f32_32x32x16_bf16 v[50:65], v[242:245], v[250:253], v[50:65]
	v_lshl_add_u64 v[254:255], v[80:81], 0, s[18:19]
	s_mov_b32 m0, s38
	s_nop 0
	global_load_lds_dwordx4 v[254:255], off sc1
	v_mfma_f32_32x32x16_bf16 v[2:17], v[246:249], v[250:253], v[2:17]
	s_waitcnt lgkmcnt(0)
	ds_read_b128 v[238:241], v95 offset:49152
	ds_read_b128 v[242:245], v97 offset:32768
	ds_read_b128 v[246:249], v97 offset:36864
	ds_read_b128 v[250:253], v95 offset:53248
	v_mfma_f32_32x32x16_bf16 v[34:49], v[106:109], v[102:105], v[34:49]
	v_lshl_add_u64 v[254:255], v[82:83], 0, s[18:19]
	s_mov_b32 m0, s39
	s_nop 0
	global_load_lds_dwordx4 v[254:255], off
	v_mfma_f32_32x32x16_bf16 v[18:33], v[110:113], v[102:105], v[18:33]
	v_lshl_add_u64 v[254:255], v[84:85], 0, s[18:19]
	s_mov_b32 m0, s50
	s_nop 0
	global_load_lds_dwordx4 v[254:255], off sc1
	v_mfma_f32_32x32x16_bf16 v[50:65], v[106:109], v[114:117], v[50:65]
	v_mfma_f32_32x32x16_bf16 v[2:17], v[110:113], v[114:117], v[2:17]
	s_waitcnt lgkmcnt(0)
	ds_read_b128 v[102:105], v98 offset:49152
	ds_read_b128 v[106:109], v99 offset:32768
	ds_read_b128 v[110:113], v99 offset:36864
	ds_read_b128 v[114:117], v98 offset:53248
	v_mfma_f32_32x32x16_bf16 v[34:49], v[242:245], v[238:241], v[34:49]
	v_lshl_add_u64 v[254:255], v[86:87], 0, s[18:19]
	s_mov_b32 m0, s51
	s_nop 0
	global_load_lds_dwordx4 v[254:255], off
	v_mfma_f32_32x32x16_bf16 v[18:33], v[246:249], v[238:241], v[18:33]
	v_lshl_add_u64 v[254:255], v[88:89], 0, s[18:19]
	s_mov_b32 m0, s83
	s_nop 0
	global_load_lds_dwordx4 v[254:255], off sc1
	v_mfma_f32_32x32x16_bf16 v[50:65], v[242:245], v[250:253], v[50:65]
	v_mfma_f32_32x32x16_bf16 v[2:17], v[246:249], v[250:253], v[2:17]
	s_waitcnt lgkmcnt(0)
	ds_read_b128 v[238:241], v100 offset:49152
	ds_read_b128 v[242:245], v101 offset:32768
	ds_read_b128 v[246:249], v101 offset:36864
	ds_read_b128 v[250:253], v100 offset:53248
	v_mfma_f32_32x32x16_bf16 v[34:49], v[106:109], v[102:105], v[34:49]
	v_lshl_add_u64 v[254:255], v[90:91], 0, s[18:19]
	s_mov_b32 m0, s90
	s_nop 0
	global_load_lds_dwordx4 v[254:255], off
	v_mfma_f32_32x32x16_bf16 v[18:33], v[110:113], v[102:105], v[18:33]
	v_mfma_f32_32x32x16_bf16 v[50:65], v[106:109], v[114:117], v[50:65]
	v_mfma_f32_32x32x16_bf16 v[2:17], v[110:113], v[114:117], v[2:17]
	s_mov_b32 m0, s86
	s_waitcnt vmcnt(0) lgkmcnt(0)
	s_barrier
; DI void gemm_out(const Params& p, char* lds) {
;     ...
;         for (int kt = 0; kt < 16; ++kt) {
;             if (kt + 1 < 16) OSTAGE((kt + 1) & 1, kt + 1);
;             const char* sb = lds + (kt & 1) * 28672; const char* sa = sb + 16384;
; #pragma unroll
;             for (int ks = 0; ks < 2; ++ks) {
;                 bf16x8 fw[4], fx[3];
; #pragma unroll
;                 for (int ct = 0; ct < 4; ++ct) fw[ct] = *(const bf16x8*)(sb + swz(wn * 64 + ct * 16 + q, 4 * ks + g));
; #pragma unroll
;                 for (int tt = 0; tt < 3; ++tt) fx[tt] = *(const bf16x8*)(sa + swz(wm * 48 + tt * 16 + q, 4 * ks + g));
; #pragma unroll
;                 for (int ct = 0; ct < 4; ++ct)
; #pragma unroll
;                     for (int tt = 0; tt < 3; ++tt) acc[ct][tt] = __builtin_amdgcn_mfma_f32_16x16x32_bf16(fw[ct], fx[tt], acc[ct][tt], 0, 0, 0);
;             }
;             __syncthreads();
;         }
	ds_read_b128 v[102:105], v74 offset:16384
	ds_read_b128 v[106:109], v96
	ds_read_b128 v[110:113], v96 offset:4096
	ds_read_b128 v[114:117], v74 offset:20480
	v_mfma_f32_32x32x16_bf16 v[34:49], v[242:245], v[238:241], v[34:49]
	v_mfma_f32_32x32x16_bf16 v[18:33], v[246:249], v[238:241], v[18:33]
	v_lshl_add_u64 v[254:255], v[76:77], 0, s[20:21]
	global_load_lds_dwordx4 v[254:255], off sc1
	v_lshl_add_u64 v[254:255], v[78:79], 0, s[20:21]
	s_mov_b32 m0, s87
	s_nop 0
	global_load_lds_dwordx4 v[254:255], off
	v_mfma_f32_32x32x16_bf16 v[50:65], v[242:245], v[250:253], v[50:65]
	v_lshl_add_u64 v[254:255], v[80:81], 0, s[20:21]
	s_mov_b32 m0, s88
	s_nop 0
	global_load_lds_dwordx4 v[254:255], off sc1
	v_mfma_f32_32x32x16_bf16 v[2:17], v[246:249], v[250:253], v[2:17]
	s_waitcnt lgkmcnt(0)
	ds_read_b128 v[238:241], v95 offset:16384
	ds_read_b128 v[242:245], v97
	ds_read_b128 v[246:249], v97 offset:4096
	ds_read_b128 v[250:253], v95 offset:20480
	v_mfma_f32_32x32x16_bf16 v[34:49], v[106:109], v[102:105], v[34:49]
	v_lshl_add_u64 v[254:255], v[82:83], 0, s[20:21]
	s_mov_b32 m0, s89
	s_nop 0
	global_load_lds_dwordx4 v[254:255], off
	v_mfma_f32_32x32x16_bf16 v[18:33], v[110:113], v[102:105], v[18:33]
	v_lshl_add_u64 v[254:255], v[84:85], 0, s[20:21]
	s_mov_b32 m0, s91
	s_nop 0
	global_load_lds_dwordx4 v[254:255], off sc1
	v_mfma_f32_32x32x16_bf16 v[50:65], v[106:109], v[114:117], v[50:65]
	v_mfma_f32_32x32x16_bf16 v[2:17], v[110:113], v[114:117], v[2:17]
	s_waitcnt lgkmcnt(0)
	ds_read_b128 v[102:105], v98 offset:16384
	ds_read_b128 v[106:109], v99
	ds_read_b128 v[110:113], v99 offset:4096
	ds_read_b128 v[114:117], v98 offset:20480
	v_mfma_f32_32x32x16_bf16 v[34:49], v[242:245], v[238:241], v[34:49]
	v_lshl_add_u64 v[254:255], v[86:87], 0, s[20:21]
	s_mov_b32 m0, s92
	s_nop 0
	global_load_lds_dwordx4 v[254:255], off
	v_mfma_f32_32x32x16_bf16 v[18:33], v[246:249], v[238:241], v[18:33]
	v_lshl_add_u64 v[254:255], v[88:89], 0, s[20:21]
	s_mov_b32 m0, s93
	s_nop 0
	global_load_lds_dwordx4 v[254:255], off sc1
	v_mfma_f32_32x32x16_bf16 v[50:65], v[242:245], v[250:253], v[50:65]
	v_mfma_f32_32x32x16_bf16 v[2:17], v[246:249], v[250:253], v[2:17]
	s_waitcnt lgkmcnt(0)
	ds_read_b128 v[238:241], v100 offset:16384
	ds_read_b128 v[242:245], v101
	ds_read_b128 v[246:249], v101 offset:4096
	ds_read_b128 v[250:253], v100 offset:20480
	v_mfma_f32_32x32x16_bf16 v[34:49], v[106:109], v[102:105], v[34:49]
	v_lshl_add_u64 v[254:255], v[90:91], 0, s[20:21]
	s_mov_b32 m0, s94
	s_nop 0
	global_load_lds_dwordx4 v[254:255], off
	v_mfma_f32_32x32x16_bf16 v[18:33], v[110:113], v[102:105], v[18:33]
	v_mfma_f32_32x32x16_bf16 v[50:65], v[106:109], v[114:117], v[50:65]
	v_mfma_f32_32x32x16_bf16 v[2:17], v[110:113], v[114:117], v[2:17]
	s_mov_b32 m0, s1
	s_waitcnt vmcnt(0) lgkmcnt(0)
	s_barrier
	ds_read_b128 v[102:105], v74 offset:49152
	ds_read_b128 v[106:109], v96 offset:32768
	ds_read_b128 v[110:113], v96 offset:36864
	ds_read_b128 v[114:117], v74 offset:53248
	v_mfma_f32_32x32x16_bf16 v[34:49], v[242:245], v[238:241], v[34:49]
	v_mfma_f32_32x32x16_bf16 v[18:33], v[246:249], v[238:241], v[18:33]
	v_lshl_add_u64 v[254:255], v[76:77], 0, s[22:23]
	global_load_lds_dwordx4 v[254:255], off sc1
	v_lshl_add_u64 v[254:255], v[78:79], 0, s[22:23]
	s_mov_b32 m0, s7
	s_nop 0
	global_load_lds_dwordx4 v[254:255], off
	v_mfma_f32_32x32x16_bf16 v[50:65], v[242:245], v[250:253], v[50:65]
	v_lshl_add_u64 v[254:255], v[80:81], 0, s[22:23]
	s_mov_b32 m0, s38
	s_nop 0
	global_load_lds_dwordx4 v[254:255], off sc1
	v_mfma_f32_32x32x16_bf16 v[2:17], v[246:249], v[250:253], v[2:17]
	s_waitcnt lgkmcnt(0)
	ds_read_b128 v[238:241], v95 offset:49152
	ds_read_b128 v[242:245], v97 offset:32768
	ds_read_b128 v[246:249], v97 offset:36864
	ds_read_b128 v[250:253], v95 offset:53248
	v_mfma_f32_32x32x16_bf16 v[34:49], v[106:109], v[102:105], v[34:49]
	v_lshl_add_u64 v[254:255], v[82:83], 0, s[22:23]
	s_mov_b32 m0, s39
	s_nop 0
	global_load_lds_dwordx4 v[254:255], off
	v_mfma_f32_32x32x16_bf16 v[18:33], v[110:113], v[102:105], v[18:33]
	v_lshl_add_u64 v[254:255], v[84:85], 0, s[22:23]
	s_mov_b32 m0, s50
	s_nop 0
	global_load_lds_dwordx4 v[254:255], off sc1
	v_mfma_f32_32x32x16_bf16 v[50:65], v[106:109], v[114:117], v[50:65]
	v_mfma_f32_32x32x16_bf16 v[2:17], v[110:113], v[114:117], v[2:17]
	s_waitcnt lgkmcnt(0)
	ds_read_b128 v[102:105], v98 offset:49152
	ds_read_b128 v[106:109], v99 offset:32768
	ds_read_b128 v[110:113], v99 offset:36864
	ds_read_b128 v[114:117], v98 offset:53248
	v_mfma_f32_32x32x16_bf16 v[34:49], v[242:245], v[238:241], v[34:49]
	v_lshl_add_u64 v[254:255], v[86:87], 0, s[22:23]
	s_mov_b32 m0, s51
	s_nop 0
	global_load_lds_dwordx4 v[254:255], off
	v_mfma_f32_32x32x16_bf16 v[18:33], v[246:249], v[238:241], v[18:33]
	v_lshl_add_u64 v[254:255], v[88:89], 0, s[22:23]
	s_mov_b32 m0, s83
	s_nop 0
	global_load_lds_dwordx4 v[254:255], off sc1
	v_mfma_f32_32x32x16_bf16 v[50:65], v[242:245], v[250:253], v[50:65]
	v_mfma_f32_32x32x16_bf16 v[2:17], v[246:249], v[250:253], v[2:17]
	s_waitcnt lgkmcnt(0)
	ds_read_b128 v[238:241], v100 offset:49152
	ds_read_b128 v[242:245], v101 offset:32768
	ds_read_b128 v[246:249], v101 offset:36864
	ds_read_b128 v[250:253], v100 offset:53248
	v_mfma_f32_32x32x16_bf16 v[34:49], v[106:109], v[102:105], v[34:49]
	v_lshl_add_u64 v[254:255], v[90:91], 0, s[22:23]
	s_mov_b32 m0, s90
	s_nop 0
	global_load_lds_dwordx4 v[254:255], off
	v_mfma_f32_32x32x16_bf16 v[18:33], v[110:113], v[102:105], v[18:33]
	v_mfma_f32_32x32x16_bf16 v[50:65], v[106:109], v[114:117], v[50:65]
	v_mfma_f32_32x32x16_bf16 v[2:17], v[110:113], v[114:117], v[2:17]
	s_mov_b32 m0, s86
	s_waitcnt vmcnt(0) lgkmcnt(0)
	s_barrier
; DI void gemm_out(const Params& p, char* lds) {
;     ...
;         for (int kt = 0; kt < 16; ++kt) {
;             if (kt + 1 < 16) OSTAGE((kt + 1) & 1, kt + 1);
;             const char* sb = lds + (kt & 1) * 28672; const char* sa = sb + 16384;
; #pragma unroll
;             for (int ks = 0; ks < 2; ++ks) {
;                 bf16x8 fw[4], fx[3];
; #pragma unroll
;                 for (int ct = 0; ct < 4; ++ct) fw[ct] = *(const bf16x8*)(sb + swz(wn * 64 + ct * 16 + q, 4 * ks + g));
; #pragma unroll
;                 for (int tt = 0; tt < 3; ++tt) fx[tt] = *(const bf16x8*)(sa + swz(wm * 48 + tt * 16 + q, 4 * ks + g));
; #pragma unroll
;                 for (int ct = 0; ct < 4; ++ct)
; #pragma unroll
;                     for (int tt = 0; tt < 3; ++tt) acc[ct][tt] = __builtin_amdgcn_mfma_f32_16x16x32_bf16(fw[ct], fx[tt], acc[ct][tt], 0, 0, 0);
;             }
;             __syncthreads();
;         }
	ds_read_b128 v[102:105], v74 offset:16384
	ds_read_b128 v[106:109], v96
	ds_read_b128 v[110:113], v96 offset:4096
	ds_read_b128 v[114:117], v74 offset:20480
	v_mfma_f32_32x32x16_bf16 v[34:49], v[242:245], v[238:241], v[34:49]
	v_mfma_f32_32x32x16_bf16 v[18:33], v[246:249], v[238:241], v[18:33]
	v_lshl_add_u64 v[254:255], v[76:77], 0, s[24:25]
	global_load_lds_dwordx4 v[254:255], off sc1
	v_lshl_add_u64 v[254:255], v[78:79], 0, s[24:25]
	s_mov_b32 m0, s87
	s_nop 0
	global_load_lds_dwordx4 v[254:255], off
	v_mfma_f32_32x32x16_bf16 v[50:65], v[242:245], v[250:253], v[50:65]
	v_lshl_add_u64 v[254:255], v[80:81], 0, s[24:25]
	s_mov_b32 m0, s88
	s_nop 0
	global_load_lds_dwordx4 v[254:255], off sc1
	v_mfma_f32_32x32x16_bf16 v[2:17], v[246:249], v[250:253], v[2:17]
	s_waitcnt lgkmcnt(0)
	ds_read_b128 v[238:241], v95 offset:16384
	ds_read_b128 v[242:245], v97
	ds_read_b128 v[246:249], v97 offset:4096
	ds_read_b128 v[250:253], v95 offset:20480
	v_mfma_f32_32x32x16_bf16 v[34:49], v[106:109], v[102:105], v[34:49]
	v_lshl_add_u64 v[254:255], v[82:83], 0, s[24:25]
	s_mov_b32 m0, s89
	s_nop 0
	global_load_lds_dwordx4 v[254:255], off
	v_mfma_f32_32x32x16_bf16 v[18:33], v[110:113], v[102:105], v[18:33]
	v_lshl_add_u64 v[254:255], v[84:85], 0, s[24:25]
	s_mov_b32 m0, s91
	s_nop 0
	global_load_lds_dwordx4 v[254:255], off sc1
	v_mfma_f32_32x32x16_bf16 v[50:65], v[106:109], v[114:117], v[50:65]
	v_mfma_f32_32x32x16_bf16 v[2:17], v[110:113], v[114:117], v[2:17]
	s_waitcnt lgkmcnt(0)
	ds_read_b128 v[102:105], v98 offset:16384
	ds_read_b128 v[106:109], v99
	ds_read_b128 v[110:113], v99 offset:4096
	ds_read_b128 v[114:117], v98 offset:20480
	v_mfma_f32_32x32x16_bf16 v[34:49], v[242:245], v[238:241], v[34:49]
	v_lshl_add_u64 v[254:255], v[86:87], 0, s[24:25]
	s_mov_b32 m0, s92
	s_nop 0
	global_load_lds_dwordx4 v[254:255], off
	v_mfma_f32_32x32x16_bf16 v[18:33], v[246:249], v[238:241], v[18:33]
	v_lshl_add_u64 v[254:255], v[88:89], 0, s[24:25]
	s_mov_b32 m0, s93
	s_nop 0
	global_load_lds_dwordx4 v[254:255], off sc1
	v_mfma_f32_32x32x16_bf16 v[50:65], v[242:245], v[250:253], v[50:65]
	v_mfma_f32_32x32x16_bf16 v[2:17], v[246:249], v[250:253], v[2:17]
	s_waitcnt lgkmcnt(0)
	ds_read_b128 v[238:241], v100 offset:16384
	ds_read_b128 v[242:245], v101
	ds_read_b128 v[246:249], v101 offset:4096
	ds_read_b128 v[250:253], v100 offset:20480
	v_mfma_f32_32x32x16_bf16 v[34:49], v[106:109], v[102:105], v[34:49]
	v_lshl_add_u64 v[254:255], v[90:91], 0, s[24:25]
	s_mov_b32 m0, s94
	s_nop 0
	global_load_lds_dwordx4 v[254:255], off
	v_mfma_f32_32x32x16_bf16 v[18:33], v[110:113], v[102:105], v[18:33]
	v_mfma_f32_32x32x16_bf16 v[50:65], v[106:109], v[114:117], v[50:65]
	v_mfma_f32_32x32x16_bf16 v[2:17], v[110:113], v[114:117], v[2:17]
	s_mov_b32 m0, s1
	s_waitcnt vmcnt(0) lgkmcnt(0)
	s_barrier
	ds_read_b128 v[102:105], v74 offset:49152
	ds_read_b128 v[106:109], v96 offset:32768
	ds_read_b128 v[110:113], v96 offset:36864
	ds_read_b128 v[114:117], v74 offset:53248
	v_mfma_f32_32x32x16_bf16 v[34:49], v[242:245], v[238:241], v[34:49]
	v_mfma_f32_32x32x16_bf16 v[18:33], v[246:249], v[238:241], v[18:33]
	v_lshl_add_u64 v[254:255], v[76:77], 0, s[26:27]
	global_load_lds_dwordx4 v[254:255], off sc1
	v_lshl_add_u64 v[254:255], v[78:79], 0, s[26:27]
	s_mov_b32 m0, s7
	s_nop 0
	global_load_lds_dwordx4 v[254:255], off
	v_mfma_f32_32x32x16_bf16 v[50:65], v[242:245], v[250:253], v[50:65]
	v_lshl_add_u64 v[254:255], v[80:81], 0, s[26:27]
	s_mov_b32 m0, s38
	s_nop 0
	global_load_lds_dwordx4 v[254:255], off sc1
	v_mfma_f32_32x32x16_bf16 v[2:17], v[246:249], v[250:253], v[2:17]
	s_waitcnt lgkmcnt(0)
	ds_read_b128 v[238:241], v95 offset:49152
	ds_read_b128 v[242:245], v97 offset:32768
	ds_read_b128 v[246:249], v97 offset:36864
	ds_read_b128 v[250:253], v95 offset:53248
	v_mfma_f32_32x32x16_bf16 v[34:49], v[106:109], v[102:105], v[34:49]
	v_lshl_add_u64 v[254:255], v[82:83], 0, s[26:27]
	s_mov_b32 m0, s39
	s_nop 0
	global_load_lds_dwordx4 v[254:255], off
	v_mfma_f32_32x32x16_bf16 v[18:33], v[110:113], v[102:105], v[18:33]
	v_lshl_add_u64 v[254:255], v[84:85], 0, s[26:27]
	s_mov_b32 m0, s50
	s_nop 0
	global_load_lds_dwordx4 v[254:255], off sc1
	v_mfma_f32_32x32x16_bf16 v[50:65], v[106:109], v[114:117], v[50:65]
	v_mfma_f32_32x32x16_bf16 v[2:17], v[110:113], v[114:117], v[2:17]
	s_waitcnt lgkmcnt(0)
	ds_read_b128 v[102:105], v98 offset:49152
	ds_read_b128 v[106:109], v99 offset:32768
	ds_read_b128 v[110:113], v99 offset:36864
	ds_read_b128 v[114:117], v98 offset:53248
	v_mfma_f32_32x32x16_bf16 v[34:49], v[242:245], v[238:241], v[34:49]
	v_lshl_add_u64 v[254:255], v[86:87], 0, s[26:27]
	s_mov_b32 m0, s51
	s_nop 0
	global_load_lds_dwordx4 v[254:255], off
	v_mfma_f32_32x32x16_bf16 v[18:33], v[246:249], v[238:241], v[18:33]
	v_lshl_add_u64 v[254:255], v[88:89], 0, s[26:27]
	s_mov_b32 m0, s83
	s_nop 0
	global_load_lds_dwordx4 v[254:255], off sc1
	v_mfma_f32_32x32x16_bf16 v[50:65], v[242:245], v[250:253], v[50:65]
	v_mfma_f32_32x32x16_bf16 v[2:17], v[246:249], v[250:253], v[2:17]
	s_waitcnt lgkmcnt(0)
	ds_read_b128 v[238:241], v100 offset:49152
	ds_read_b128 v[242:245], v101 offset:32768
	ds_read_b128 v[246:249], v101 offset:36864
	ds_read_b128 v[250:253], v100 offset:53248
	v_mfma_f32_32x32x16_bf16 v[34:49], v[106:109], v[102:105], v[34:49]
	v_lshl_add_u64 v[254:255], v[90:91], 0, s[26:27]
	s_mov_b32 m0, s90
	s_nop 0
	global_load_lds_dwordx4 v[254:255], off
	v_mfma_f32_32x32x16_bf16 v[18:33], v[110:113], v[102:105], v[18:33]
	v_mfma_f32_32x32x16_bf16 v[50:65], v[106:109], v[114:117], v[50:65]
	v_mfma_f32_32x32x16_bf16 v[2:17], v[110:113], v[114:117], v[2:17]
	s_mov_b32 m0, s86
	s_waitcnt vmcnt(0) lgkmcnt(0)
	s_barrier
; DI void gemm_out(const Params& p, char* lds) {
;     ...
;         for (int kt = 0; kt < 16; ++kt) {
;             if (kt + 1 < 16) OSTAGE((kt + 1) & 1, kt + 1);
;             const char* sb = lds + (kt & 1) * 28672; const char* sa = sb + 16384;
; #pragma unroll
;             for (int ks = 0; ks < 2; ++ks) {
;                 bf16x8 fw[4], fx[3];
; #pragma unroll
;                 for (int ct = 0; ct < 4; ++ct) fw[ct] = *(const bf16x8*)(sb + swz(wn * 64 + ct * 16 + q, 4 * ks + g));
; #pragma unroll
;                 for (int tt = 0; tt < 3; ++tt) fx[tt] = *(const bf16x8*)(sa + swz(wm * 48 + tt * 16 + q, 4 * ks + g));
; #pragma unroll
;                 for (int ct = 0; ct < 4; ++ct)
; #pragma unroll
;                     for (int tt = 0; tt < 3; ++tt) acc[ct][tt] = __builtin_amdgcn_mfma_f32_16x16x32_bf16(fw[ct], fx[tt], acc[ct][tt], 0, 0, 0);
;             }
;             __syncthreads();
;         }
	ds_read_b128 v[102:105], v74 offset:16384
	ds_read_b128 v[106:109], v96
	ds_read_b128 v[110:113], v96 offset:4096
	ds_read_b128 v[114:117], v74 offset:20480
	v_mfma_f32_32x32x16_bf16 v[34:49], v[242:245], v[238:241], v[34:49]
	v_mfma_f32_32x32x16_bf16 v[18:33], v[246:249], v[238:241], v[18:33]
	v_lshl_add_u64 v[254:255], v[76:77], 0, s[28:29]
	global_load_lds_dwordx4 v[254:255], off sc1
	v_lshl_add_u64 v[254:255], v[78:79], 0, s[28:29]
	s_mov_b32 m0, s87
	s_nop 0
	global_load_lds_dwordx4 v[254:255], off
	v_mfma_f32_32x32x16_bf16 v[50:65], v[242:245], v[250:253], v[50:65]
	v_lshl_add_u64 v[254:255], v[80:81], 0, s[28:29]
	s_mov_b32 m0, s88
	s_nop 0
	global_load_lds_dwordx4 v[254:255], off sc1
	v_mfma_f32_32x32x16_bf16 v[2:17], v[246:249], v[250:253], v[2:17]
	s_waitcnt lgkmcnt(0)
	ds_read_b128 v[238:241], v95 offset:16384
	ds_read_b128 v[242:245], v97
	ds_read_b128 v[246:249], v97 offset:4096
	ds_read_b128 v[250:253], v95 offset:20480
	v_mfma_f32_32x32x16_bf16 v[34:49], v[106:109], v[102:105], v[34:49]
	v_lshl_add_u64 v[254:255], v[82:83], 0, s[28:29]
	s_mov_b32 m0, s89
	s_nop 0
	global_load_lds_dwordx4 v[254:255], off
	v_mfma_f32_32x32x16_bf16 v[18:33], v[110:113], v[102:105], v[18:33]
	v_lshl_add_u64 v[254:255], v[84:85], 0, s[28:29]
	s_mov_b32 m0, s91
	s_nop 0
	global_load_lds_dwordx4 v[254:255], off sc1
	v_mfma_f32_32x32x16_bf16 v[50:65], v[106:109], v[114:117], v[50:65]
	v_mfma_f32_32x32x16_bf16 v[2:17], v[110:113], v[114:117], v[2:17]
	s_waitcnt lgkmcnt(0)
	ds_read_b128 v[102:105], v98 offset:16384
	ds_read_b128 v[106:109], v99
	ds_read_b128 v[110:113], v99 offset:4096
	ds_read_b128 v[114:117], v98 offset:20480
	v_mfma_f32_32x32x16_bf16 v[34:49], v[242:245], v[238:241], v[34:49]
	v_lshl_add_u64 v[254:255], v[86:87], 0, s[28:29]
	s_mov_b32 m0, s92
	s_nop 0
	global_load_lds_dwordx4 v[254:255], off
	v_mfma_f32_32x32x16_bf16 v[18:33], v[246:249], v[238:241], v[18:33]
	v_lshl_add_u64 v[254:255], v[88:89], 0, s[28:29]
	s_mov_b32 m0, s93
	s_nop 0
	global_load_lds_dwordx4 v[254:255], off sc1
	v_mfma_f32_32x32x16_bf16 v[50:65], v[242:245], v[250:253], v[50:65]
	v_mfma_f32_32x32x16_bf16 v[2:17], v[246:249], v[250:253], v[2:17]
	s_waitcnt lgkmcnt(0)
	ds_read_b128 v[238:241], v100 offset:16384
	ds_read_b128 v[242:245], v101
	ds_read_b128 v[246:249], v101 offset:4096
	ds_read_b128 v[250:253], v100 offset:20480
	v_mfma_f32_32x32x16_bf16 v[34:49], v[106:109], v[102:105], v[34:49]
	v_lshl_add_u64 v[254:255], v[90:91], 0, s[28:29]
	s_mov_b32 m0, s94
	s_nop 0
	global_load_lds_dwordx4 v[254:255], off
	v_mfma_f32_32x32x16_bf16 v[18:33], v[110:113], v[102:105], v[18:33]
	v_mfma_f32_32x32x16_bf16 v[50:65], v[106:109], v[114:117], v[50:65]
	v_mfma_f32_32x32x16_bf16 v[2:17], v[110:113], v[114:117], v[2:17]
	s_mov_b32 m0, s1
	s_waitcnt vmcnt(0) lgkmcnt(0)
	s_barrier
	ds_read_b128 v[102:105], v74 offset:49152
	ds_read_b128 v[106:109], v96 offset:32768
	ds_read_b128 v[110:113], v96 offset:36864
	ds_read_b128 v[114:117], v74 offset:53248
	v_mfma_f32_32x32x16_bf16 v[34:49], v[242:245], v[238:241], v[34:49]
	v_mfma_f32_32x32x16_bf16 v[18:33], v[246:249], v[238:241], v[18:33]
	v_lshl_add_u64 v[254:255], v[76:77], 0, s[30:31]
	global_load_lds_dwordx4 v[254:255], off sc1
	v_lshl_add_u64 v[254:255], v[78:79], 0, s[30:31]
	s_mov_b32 m0, s7
	s_nop 0
	global_load_lds_dwordx4 v[254:255], off
	v_mfma_f32_32x32x16_bf16 v[50:65], v[242:245], v[250:253], v[50:65]
	v_lshl_add_u64 v[254:255], v[80:81], 0, s[30:31]
	s_mov_b32 m0, s38
	s_nop 0
	global_load_lds_dwordx4 v[254:255], off sc1
	v_mfma_f32_32x32x16_bf16 v[2:17], v[246:249], v[250:253], v[2:17]
	s_waitcnt lgkmcnt(0)
	ds_read_b128 v[238:241], v95 offset:49152
	ds_read_b128 v[242:245], v97 offset:32768
	ds_read_b128 v[246:249], v97 offset:36864
	ds_read_b128 v[250:253], v95 offset:53248
	v_mfma_f32_32x32x16_bf16 v[34:49], v[106:109], v[102:105], v[34:49]
	v_lshl_add_u64 v[254:255], v[82:83], 0, s[30:31]
	s_mov_b32 m0, s39
	s_nop 0
	global_load_lds_dwordx4 v[254:255], off
	v_mfma_f32_32x32x16_bf16 v[18:33], v[110:113], v[102:105], v[18:33]
	v_lshl_add_u64 v[254:255], v[84:85], 0, s[30:31]
	s_mov_b32 m0, s50
	s_nop 0
	global_load_lds_dwordx4 v[254:255], off sc1
	v_mfma_f32_32x32x16_bf16 v[50:65], v[106:109], v[114:117], v[50:65]
	v_mfma_f32_32x32x16_bf16 v[2:17], v[110:113], v[114:117], v[2:17]
	s_waitcnt lgkmcnt(0)
	ds_read_b128 v[102:105], v98 offset:49152
	ds_read_b128 v[106:109], v99 offset:32768
	ds_read_b128 v[110:113], v99 offset:36864
	ds_read_b128 v[114:117], v98 offset:53248
	v_mfma_f32_32x32x16_bf16 v[34:49], v[242:245], v[238:241], v[34:49]
	v_lshl_add_u64 v[254:255], v[86:87], 0, s[30:31]
	s_mov_b32 m0, s51
	s_nop 0
	global_load_lds_dwordx4 v[254:255], off
	v_mfma_f32_32x32x16_bf16 v[18:33], v[246:249], v[238:241], v[18:33]
	v_lshl_add_u64 v[254:255], v[88:89], 0, s[30:31]
	s_mov_b32 m0, s83
	s_nop 0
	global_load_lds_dwordx4 v[254:255], off sc1
	v_mfma_f32_32x32x16_bf16 v[50:65], v[242:245], v[250:253], v[50:65]
	v_mfma_f32_32x32x16_bf16 v[2:17], v[246:249], v[250:253], v[2:17]
	s_waitcnt lgkmcnt(0)
	ds_read_b128 v[238:241], v100 offset:49152
	ds_read_b128 v[242:245], v101 offset:32768
	ds_read_b128 v[246:249], v101 offset:36864
	ds_read_b128 v[250:253], v100 offset:53248
	v_mfma_f32_32x32x16_bf16 v[34:49], v[106:109], v[102:105], v[34:49]
	v_lshl_add_u64 v[254:255], v[90:91], 0, s[30:31]
	s_mov_b32 m0, s90
	s_nop 0
	global_load_lds_dwordx4 v[254:255], off
	v_mfma_f32_32x32x16_bf16 v[18:33], v[110:113], v[102:105], v[18:33]
	v_mfma_f32_32x32x16_bf16 v[50:65], v[106:109], v[114:117], v[50:65]
	v_mfma_f32_32x32x16_bf16 v[2:17], v[110:113], v[114:117], v[2:17]
	s_mov_b32 m0, s86
	s_waitcnt vmcnt(0) lgkmcnt(0)
	s_barrier
; DI void gemm_out(const Params& p, char* lds) {
;     ...
;         for (int kt = 0; kt < 16; ++kt) {
;             if (kt + 1 < 16) OSTAGE((kt + 1) & 1, kt + 1);
;             const char* sb = lds + (kt & 1) * 28672; const char* sa = sb + 16384;
; #pragma unroll
;             for (int ks = 0; ks < 2; ++ks) {
;                 bf16x8 fw[4], fx[3];
; #pragma unroll
;                 for (int ct = 0; ct < 4; ++ct) fw[ct] = *(const bf16x8*)(sb + swz(wn * 64 + ct * 16 + q, 4 * ks + g));
; #pragma unroll
;                 for (int tt = 0; tt < 3; ++tt) fx[tt] = *(const bf16x8*)(sa + swz(wm * 48 + tt * 16 + q, 4 * ks + g));
; #pragma unroll
;                 for (int ct = 0; ct < 4; ++ct)
; #pragma unroll
;                     for (int tt = 0; tt < 3; ++tt) acc[ct][tt] = __builtin_amdgcn_mfma_f32_16x16x32_bf16(fw[ct], fx[tt], acc[ct][tt], 0, 0, 0);
;             }
;             __syncthreads();
;         }
	ds_read_b128 v[102:105], v74 offset:16384
	ds_read_b128 v[106:109], v96
	ds_read_b128 v[110:113], v96 offset:4096
	ds_read_b128 v[114:117], v74 offset:20480
	v_mfma_f32_32x32x16_bf16 v[34:49], v[242:245], v[238:241], v[34:49]
	v_mfma_f32_32x32x16_bf16 v[18:33], v[246:249], v[238:241], v[18:33]
	v_lshl_add_u64 v[254:255], v[76:77], 0, s[36:37]
	global_load_lds_dwordx4 v[254:255], off sc1
	v_lshl_add_u64 v[254:255], v[78:79], 0, s[36:37]
	s_mov_b32 m0, s87
	s_nop 0
	global_load_lds_dwordx4 v[254:255], off
	v_mfma_f32_32x32x16_bf16 v[50:65], v[242:245], v[250:253], v[50:65]
	v_lshl_add_u64 v[254:255], v[80:81], 0, s[36:37]
	s_mov_b32 m0, s88
	s_nop 0
	global_load_lds_dwordx4 v[254:255], off sc1
	v_mfma_f32_32x32x16_bf16 v[2:17], v[246:249], v[250:253], v[2:17]
	s_waitcnt lgkmcnt(0)
	ds_read_b128 v[238:241], v95 offset:16384
	ds_read_b128 v[242:245], v97
	ds_read_b128 v[246:249], v97 offset:4096
	ds_read_b128 v[250:253], v95 offset:20480
	v_mfma_f32_32x32x16_bf16 v[34:49], v[106:109], v[102:105], v[34:49]
	v_lshl_add_u64 v[254:255], v[82:83], 0, s[36:37]
	s_mov_b32 m0, s89
	s_nop 0
	global_load_lds_dwordx4 v[254:255], off
	v_mfma_f32_32x32x16_bf16 v[18:33], v[110:113], v[102:105], v[18:33]
	v_lshl_add_u64 v[254:255], v[84:85], 0, s[36:37]
	s_mov_b32 m0, s91
	s_nop 0
	global_load_lds_dwordx4 v[254:255], off sc1
	v_mfma_f32_32x32x16_bf16 v[50:65], v[106:109], v[114:117], v[50:65]
	v_mfma_f32_32x32x16_bf16 v[2:17], v[110:113], v[114:117], v[2:17]
	s_waitcnt lgkmcnt(0)
	ds_read_b128 v[102:105], v98 offset:16384
	ds_read_b128 v[106:109], v99
	ds_read_b128 v[110:113], v99 offset:4096
	ds_read_b128 v[114:117], v98 offset:20480
	v_mfma_f32_32x32x16_bf16 v[34:49], v[242:245], v[238:241], v[34:49]
	v_lshl_add_u64 v[254:255], v[86:87], 0, s[36:37]
	s_mov_b32 m0, s92
	s_nop 0
	global_load_lds_dwordx4 v[254:255], off
	v_mfma_f32_32x32x16_bf16 v[18:33], v[246:249], v[238:241], v[18:33]
	v_lshl_add_u64 v[254:255], v[88:89], 0, s[36:37]
	s_mov_b32 m0, s93
	s_nop 0
	global_load_lds_dwordx4 v[254:255], off sc1
	v_mfma_f32_32x32x16_bf16 v[50:65], v[242:245], v[250:253], v[50:65]
	v_mfma_f32_32x32x16_bf16 v[2:17], v[246:249], v[250:253], v[2:17]
	s_waitcnt lgkmcnt(0)
	ds_read_b128 v[238:241], v100 offset:16384
	ds_read_b128 v[242:245], v101
	ds_read_b128 v[246:249], v101 offset:4096
	ds_read_b128 v[250:253], v100 offset:20480
	v_mfma_f32_32x32x16_bf16 v[34:49], v[106:109], v[102:105], v[34:49]
	v_lshl_add_u64 v[254:255], v[90:91], 0, s[36:37]
	s_mov_b32 m0, s94
	s_nop 0
	global_load_lds_dwordx4 v[254:255], off
	v_mfma_f32_32x32x16_bf16 v[18:33], v[110:113], v[102:105], v[18:33]
	v_mfma_f32_32x32x16_bf16 v[50:65], v[106:109], v[114:117], v[50:65]
	v_mfma_f32_32x32x16_bf16 v[2:17], v[110:113], v[114:117], v[2:17]
	s_mov_b32 m0, s1
	s_waitcnt vmcnt(0) lgkmcnt(0)
	s_barrier
	ds_read_b128 v[102:105], v74 offset:49152
	ds_read_b128 v[106:109], v96 offset:32768
	ds_read_b128 v[110:113], v96 offset:36864
	ds_read_b128 v[114:117], v74 offset:53248
	v_mfma_f32_32x32x16_bf16 v[34:49], v[242:245], v[238:241], v[34:49]
	v_mfma_f32_32x32x16_bf16 v[18:33], v[246:249], v[238:241], v[18:33]
	v_lshl_add_u64 v[254:255], v[76:77], 0, s[68:69]
	global_load_lds_dwordx4 v[254:255], off sc1
	v_lshl_add_u64 v[254:255], v[78:79], 0, s[68:69]
	s_mov_b32 m0, s7
	v_lshl_add_u64 v[76:77], v[76:77], 0, s[70:71]
	global_load_lds_dwordx4 v[254:255], off
	v_mfma_f32_32x32x16_bf16 v[50:65], v[242:245], v[250:253], v[50:65]
	v_lshl_add_u64 v[254:255], v[80:81], 0, s[68:69]
	s_mov_b32 m0, s38
	s_nop 0
	global_load_lds_dwordx4 v[254:255], off sc1
	v_mfma_f32_32x32x16_bf16 v[2:17], v[246:249], v[250:253], v[2:17]
	s_waitcnt lgkmcnt(0)
	ds_read_b128 v[238:241], v95 offset:49152
	ds_read_b128 v[242:245], v97 offset:32768
	ds_read_b128 v[246:249], v97 offset:36864
	ds_read_b128 v[250:253], v95 offset:53248
	v_mfma_f32_32x32x16_bf16 v[34:49], v[106:109], v[102:105], v[34:49]
	v_lshl_add_u64 v[254:255], v[82:83], 0, s[68:69]
	s_mov_b32 m0, s39
	s_nop 0
	global_load_lds_dwordx4 v[254:255], off
	v_mfma_f32_32x32x16_bf16 v[18:33], v[110:113], v[102:105], v[18:33]
	v_lshl_add_u64 v[254:255], v[84:85], 0, s[68:69]
	s_mov_b32 m0, s50
	s_nop 0
	global_load_lds_dwordx4 v[254:255], off sc1
	v_mfma_f32_32x32x16_bf16 v[50:65], v[106:109], v[114:117], v[50:65]
	v_mfma_f32_32x32x16_bf16 v[2:17], v[110:113], v[114:117], v[2:17]
	s_waitcnt lgkmcnt(0)
	ds_read_b128 v[102:105], v98 offset:49152
	ds_read_b128 v[106:109], v99 offset:32768
	ds_read_b128 v[110:113], v99 offset:36864
	ds_read_b128 v[114:117], v98 offset:53248
	v_mfma_f32_32x32x16_bf16 v[34:49], v[242:245], v[238:241], v[34:49]
	v_lshl_add_u64 v[254:255], v[86:87], 0, s[68:69]
	s_mov_b32 m0, s51
	s_nop 0
	global_load_lds_dwordx4 v[254:255], off
	v_mfma_f32_32x32x16_bf16 v[18:33], v[246:249], v[238:241], v[18:33]
	v_lshl_add_u64 v[254:255], v[88:89], 0, s[68:69]
	s_mov_b32 m0, s83
	s_nop 0
	global_load_lds_dwordx4 v[254:255], off sc1
	v_mfma_f32_32x32x16_bf16 v[50:65], v[242:245], v[250:253], v[50:65]
	v_mfma_f32_32x32x16_bf16 v[2:17], v[246:249], v[250:253], v[2:17]
	s_waitcnt lgkmcnt(0)
	ds_read_b128 v[238:241], v100 offset:49152
	ds_read_b128 v[242:245], v101 offset:32768
	ds_read_b128 v[246:249], v101 offset:36864
	ds_read_b128 v[250:253], v100 offset:53248
	v_mfma_f32_32x32x16_bf16 v[34:49], v[106:109], v[102:105], v[34:49]
	v_lshl_add_u64 v[254:255], v[90:91], 0, s[68:69]
	s_mov_b32 m0, s90
	s_nop 0
	global_load_lds_dwordx4 v[254:255], off
	v_mfma_f32_32x32x16_bf16 v[18:33], v[110:113], v[102:105], v[18:33]
	v_mfma_f32_32x32x16_bf16 v[50:65], v[106:109], v[114:117], v[50:65]
	v_mfma_f32_32x32x16_bf16 v[2:17], v[110:113], v[114:117], v[2:17]
	s_mov_b32 m0, s86
	s_mov_b32 s86, 0
	s_waitcnt vmcnt(0) lgkmcnt(0)
	s_barrier
; DI void gemm_out(const Params& p, char* lds) {
;     ...
;     for (int tile = vb; tile < ntile; tile += gridDim.x) {
;         int tid = threadIdx.x; asm volatile("" : "+v"(tid));
;         const int lane = tid & 63, wave = __builtin_amdgcn_readfirstlane(tid >> 6); const int wn = wave >> 1, wm = wave & 1; const int q = lane & 15, g = lane >> 4;
;         const int mt = tile >> 3, nt = tile & 7; const int m0 = mt * 96, n0 = nt * 128;
;         f32x4 acc[4][3];
; #pragma unroll
;         for (int a = 0; a < 4; ++a)
; #pragma unroll
;             for (int b = 0; b < 3; ++b) acc[a][b] = (f32x4){0.f, 0.f, 0.f, 0.f};
;         unsigned soffb[4], soffa[3];
; #pragma unroll
;         for (int i = 0; i < 4; ++i) { const int row = 8 * (i * 4 + wave) + (lane >> 3); const int ch = (lane & 7) ^ ((row >> 1) & 7); soffb[i] = (unsigned)(row * 1024 + ch * 8); }
; #pragma unroll
;         for (int i = 0; i < 3; ++i) { const int row = 8 * (i * 4 + wave) + (lane >> 3); const int ch = (lane & 7) ^ ((row >> 1) & 7); soffa[i] = (unsigned)(row * 1024 + ch * 8); }
;         const u16* ga = A + (size_t)m0 * 1024; const u16* gb = B + (size_t)n0 * 1024;
;     ...
;         OSTAGE(0, 0);
;         float4 xres[3][4];
; #pragma unroll
;         for (int tt = 0; tt < 3; ++tt) { const int row = m0 + wm * 48 + tt * 16 + q; const float* xr = row < NTP ? p.x_p + (size_t)row * DM : p.x_s + (size_t)(row - NTP) * DM;
; #pragma unroll
;             for (int ct = 0; ct < 4; ++ct) xres[tt][ct] = ntld4(xr + n0 + wn * 64 + ct * 16 + 4 * g); }
;     ...
;         for (int kt = 0; kt < 16; ++kt) {
;             if (kt + 1 < 16) OSTAGE((kt + 1) & 1, kt + 1);
;             const char* sb = lds + (kt & 1) * 28672; const char* sa = sb + 16384;
; #pragma unroll
;             for (int ks = 0; ks < 2; ++ks) {
;                 bf16x8 fw[4], fx[3];
; #pragma unroll
;                 for (int ct = 0; ct < 4; ++ct) fw[ct] = *(const bf16x8*)(sb + swz(wn * 64 + ct * 16 + q, 4 * ks + g));
; #pragma unroll
;                 for (int tt = 0; tt < 3; ++tt) fx[tt] = *(const bf16x8*)(sa + swz(wm * 48 + tt * 16 + q, 4 * ks + g));
; #pragma unroll
;                 for (int ct = 0; ct < 4; ++ct)
; #pragma unroll
;                     for (int tt = 0; tt < 3; ++tt) acc[ct][tt] = __builtin_amdgcn_mfma_f32_16x16x32_bf16(fw[ct], fx[tt], acc[ct][tt], 0, 0, 0);
;             }
;             __syncthreads();
;         }
	global_load_lds_dwordx4 v[76:77], off sc1
	v_lshl_add_u64 v[76:77], v[78:79], 0, s[70:71]
	s_mov_b32 m0, s87
	v_mfma_f32_32x32x16_bf16 v[34:49], v[242:245], v[238:241], v[34:49]
	global_load_lds_dwordx4 v[76:77], off
	v_lshl_add_u64 v[76:77], v[80:81], 0, s[70:71]
	s_mov_b32 m0, s88
	s_mov_b32 s88, 0
	global_load_lds_dwordx4 v[76:77], off sc1
	v_lshl_add_u64 v[76:77], v[82:83], 0, s[70:71]
	s_mov_b32 m0, s89
	v_mfma_f32_32x32x16_bf16 v[18:33], v[246:249], v[238:241], v[18:33]
	global_load_lds_dwordx4 v[76:77], off
	v_lshl_add_u64 v[76:77], v[84:85], 0, s[70:71]
	s_mov_b32 m0, s91
	s_nop 0
	global_load_lds_dwordx4 v[76:77], off sc1
	v_lshl_add_u64 v[76:77], v[86:87], 0, s[70:71]
	s_mov_b32 m0, s92
	v_mfma_f32_32x32x16_bf16 v[50:65], v[242:245], v[250:253], v[50:65]
	global_load_lds_dwordx4 v[76:77], off
	v_lshl_add_u64 v[76:77], v[88:89], 0, s[70:71]
	s_mov_b32 m0, s93
	s_nop 0
	global_load_lds_dwordx4 v[76:77], off sc1
	v_lshl_add_u64 v[76:77], v[90:91], 0, s[70:71]
	s_mov_b32 m0, s94
	v_mfma_f32_32x32x16_bf16 v[2:17], v[246:249], v[250:253], v[2:17]
	global_load_lds_dwordx4 v[76:77], off
	ds_read_b128 v[76:79], v74 offset:16384
	ds_read_b128 v[80:83], v96
	ds_read_b128 v[84:87], v96 offset:4096
	ds_read_b128 v[88:91], v74 offset:20480
	s_waitcnt lgkmcnt(0)
	v_mfma_f32_32x32x16_bf16 v[34:49], v[80:83], v[76:79], v[34:49]
	v_mfma_f32_32x32x16_bf16 v[18:33], v[84:87], v[76:79], v[18:33]
	v_mfma_f32_32x32x16_bf16 v[50:65], v[80:83], v[88:91], v[50:65]
	v_mfma_f32_32x32x16_bf16 v[2:17], v[84:87], v[88:91], v[2:17]
	ds_read_b128 v[76:79], v95 offset:16384
	ds_read_b128 v[80:83], v97
	ds_read_b128 v[84:87], v97 offset:4096
	ds_read_b128 v[88:91], v95 offset:20480
	s_waitcnt lgkmcnt(0)
	v_mfma_f32_32x32x16_bf16 v[34:49], v[80:83], v[76:79], v[34:49]
	v_mfma_f32_32x32x16_bf16 v[18:33], v[84:87], v[76:79], v[18:33]
	v_mfma_f32_32x32x16_bf16 v[50:65], v[80:83], v[88:91], v[50:65]
	v_mfma_f32_32x32x16_bf16 v[2:17], v[84:87], v[88:91], v[2:17]
	ds_read_b128 v[76:79], v98 offset:16384
	ds_read_b128 v[80:83], v99
	ds_read_b128 v[84:87], v99 offset:4096
	ds_read_b128 v[88:91], v98 offset:20480
	s_waitcnt lgkmcnt(0)
	v_mfma_f32_32x32x16_bf16 v[34:49], v[80:83], v[76:79], v[34:49]
	v_mfma_f32_32x32x16_bf16 v[18:33], v[84:87], v[76:79], v[18:33]
	v_mfma_f32_32x32x16_bf16 v[50:65], v[80:83], v[88:91], v[50:65]
	v_mfma_f32_32x32x16_bf16 v[2:17], v[84:87], v[88:91], v[2:17]
	ds_read_b128 v[76:79], v100 offset:16384
	ds_read_b128 v[80:83], v101
	ds_read_b128 v[84:87], v101 offset:4096
	ds_read_b128 v[88:91], v100 offset:20480
	s_waitcnt vmcnt(0) lgkmcnt(0)
	s_barrier
	s_cbranch_scc1 .Lo_skipnext
	s_mov_b32 m0, s1
	s_lshr_b32 s86, s33, 3
	s_lshl_b32 s86, s86, 7
	s_and_b32 s88, s33, 7
	s_lshl_b32 s88, s88, 7
	s_ashr_i32 s87, s86, 31
	s_lshl_b64 s[92:93], s[86:87], 11
	s_add_u32 s92, s54, s92
	s_addc_u32 s93, s55, s93
	s_ashr_i32 s89, s88, 31
	s_lshl_b64 s[94:95], s[88:89], 11
	v_readlane_b32 s1, v236, 9
	s_add_u32 s94, s1, s94
	v_readlane_b32 s1, v236, 11
	s_addc_u32 s95, s1, s95
	v_lshl_add_u64 v[118:119], s[92:93], 0, v[66:67]
	global_load_lds_dwordx4 v[118:119], off sc1
	v_lshl_add_u64 v[66:67], s[94:95], 0, v[66:67]
	s_mov_b32 m0, s7
	s_nop 0
	global_load_lds_dwordx4 v[66:67], off
	v_lshl_add_u64 v[66:67], s[92:93], 0, v[68:69]
	s_mov_b32 m0, s38
	s_nop 0
	global_load_lds_dwordx4 v[66:67], off sc1
	v_lshl_add_u64 v[66:67], s[94:95], 0, v[68:69]
	s_mov_b32 m0, s39
	s_nop 0
	global_load_lds_dwordx4 v[66:67], off
	v_lshl_add_u64 v[66:67], s[92:93], 0, v[70:71]
	s_mov_b32 m0, s50
	s_nop 0
	global_load_lds_dwordx4 v[66:67], off sc1
	v_lshl_add_u64 v[66:67], s[94:95], 0, v[70:71]
	s_mov_b32 m0, s51
	s_nop 0
	global_load_lds_dwordx4 v[66:67], off
	v_lshl_add_u64 v[66:67], s[92:93], 0, v[72:73]
	s_mov_b32 m0, s83
	s_nop 0
	global_load_lds_dwordx4 v[66:67], off sc1
	v_lshl_add_u64 v[66:67], s[94:95], 0, v[72:73]
	s_mov_b32 m0, s90
	s_nop 0
	global_load_lds_dwordx4 v[66:67], off
.Lo_skipnext:
	v_readfirstlane_b32 s96, v0
	s_lshr_b32 s96, s96, 6
	s_lshr_b32 s98, s96, 1
	s_and_b32 s96, s96, 1
	s_lshl_b32 s97, s96, 6
	s_add_i32 s97, s97, s82
	s_cmp_lt_u32 s82, 0x4000
	s_cselect_b32 s2, s56, s58
	s_cselect_b32 s3, s57, s59
	s_cselect_b32 s99, 0, 0x4000
	s_sub_i32 s99, s97, s99
	s_lshl_b32 s98, s98, 6
	s_add_i32 s98, s98, s0
	v_and_b32_e32 v184, 31, v0
	v_bfe_u32 v185, v0, 5, 1
	v_lshlrev_b32_e32 v185, 14, v185
	v_add_u32_e32 v186, s98, v184
	v_lshl_add_u32 v186, v186, 2, v185
	s_lshl_b32 s97, s97, 12
	s_lshl_b32 s99, s99, 12
	v_add_u32_e32 v188, s97, v186
	v_add_u32_e32 v187, s99, v186
	v_mfma_f32_32x32x16_bf16 v[34:49], v[80:83], v[76:79], v[34:49]
	global_load_dword v120, v187, s[2:3] nt
	global_load_dword v121, v187, s[2:3] offset:128 nt
	v_add_u32_e32 v187, 0x1000, v187
	global_load_dword v122, v187, s[2:3] nt
	global_load_dword v123, v187, s[2:3] offset:128 nt
	v_add_u32_e32 v187, 0x1000, v187
	v_mfma_f32_32x32x16_bf16 v[18:33], v[84:87], v[76:79], v[18:33]
	global_load_dword v124, v187, s[2:3] nt
	global_load_dword v125, v187, s[2:3] offset:128 nt
	v_add_u32_e32 v187, 0x1000, v187
	global_load_dword v126, v187, s[2:3] nt
	global_load_dword v127, v187, s[2:3] offset:128 nt
	v_add_u32_e32 v187, 0x5000, v187
	v_mfma_f32_32x32x16_bf16 v[50:65], v[80:83], v[88:91], v[50:65]
	global_load_dword v128, v187, s[2:3] nt
	global_load_dword v129, v187, s[2:3] offset:128 nt
	v_add_u32_e32 v187, 0x1000, v187
	global_load_dword v130, v187, s[2:3] nt
	global_load_dword v131, v187, s[2:3] offset:128 nt
	v_add_u32_e32 v187, 0x1000, v187
	v_mfma_f32_32x32x16_bf16 v[2:17], v[84:87], v[88:91], v[2:17]
	global_load_dword v132, v187, s[2:3] nt
	global_load_dword v133, v187, s[2:3] offset:128 nt
	v_add_u32_e32 v187, 0x1000, v187
	global_load_dword v134, v187, s[2:3] nt
	global_load_dword v135, v187, s[2:3] offset:128 nt
	v_add_u32_e32 v187, 0x5000, v187
	ds_read_b128 v[76:79], v96 offset:32768
	ds_read_b128 v[80:83], v96 offset:36864
	ds_read_b128 v[84:87], v74 offset:49152
	ds_read_b128 v[88:91], v74 offset:53248
	s_waitcnt lgkmcnt(1)
; DI float4 ntld4(const float* p) { const f32x4 v = __builtin_nontemporal_load((const f32x4*)p); return (float4){v[0], v[1], v[2], v[3]}; }
; DI void gemm_out(const Params& p, char* lds) {
;     ...
;         for (int tt = 0; tt < 3; ++tt) { const int row = m0 + wm * 48 + tt * 16 + q; const float* xr = row < NTP ? p.x_p + (size_t)row * DM : p.x_s + (size_t)(row - NTP) * DM;
; #pragma unroll
;             for (int ct = 0; ct < 4; ++ct) xres[tt][ct] = ntld4(xr + n0 + wn * 64 + ct * 16 + 4 * g); }
;     ...
;                 for (int tt = 0; tt < 3; ++tt) fx[tt] = *(const bf16x8*)(sa + swz(wm * 48 + tt * 16 + q, 4 * ks + g));
; #pragma unroll
;                 for (int ct = 0; ct < 4; ++ct)
; #pragma unroll
;                     for (int tt = 0; tt < 3; ++tt) acc[ct][tt] = __builtin_amdgcn_mfma_f32_16x16x32_bf16(fw[ct], fx[tt], acc[ct][tt], 0, 0, 0);
	v_mfma_f32_32x32x16_bf16 v[34:49], v[76:79], v[84:87], v[34:49]
	global_load_dword v136, v187, s[2:3] nt
	global_load_dword v137, v187, s[2:3] offset:128 nt
	v_add_u32_e32 v187, 0x1000, v187
	global_load_dword v138, v187, s[2:3] nt
	global_load_dword v139, v187, s[2:3] offset:128 nt
	v_add_u32_e32 v187, 0x1000, v187
	v_mfma_f32_32x32x16_bf16 v[18:33], v[80:83], v[84:87], v[18:33]
	global_load_dword v140, v187, s[2:3] nt
	global_load_dword v141, v187, s[2:3] offset:128 nt
	v_add_u32_e32 v187, 0x1000, v187
	global_load_dword v142, v187, s[2:3] nt
	global_load_dword v143, v187, s[2:3] offset:128 nt
	v_add_u32_e32 v187, 0x5000, v187
	s_waitcnt lgkmcnt(0)
	v_mfma_f32_32x32x16_bf16 v[50:65], v[76:79], v[88:91], v[50:65]
	global_load_dword v144, v187, s[2:3] nt
	global_load_dword v145, v187, s[2:3] offset:128 nt
	v_add_u32_e32 v187, 0x1000, v187
	global_load_dword v146, v187, s[2:3] nt
	global_load_dword v147, v187, s[2:3] offset:128 nt
	v_add_u32_e32 v187, 0x1000, v187
	v_mfma_f32_32x32x16_bf16 v[2:17], v[80:83], v[88:91], v[2:17]
	global_load_dword v148, v187, s[2:3] nt
	global_load_dword v149, v187, s[2:3] offset:128 nt
	v_add_u32_e32 v187, 0x1000, v187
	global_load_dword v150, v187, s[2:3] nt
	global_load_dword v151, v187, s[2:3] offset:128 nt
	v_add_u32_e32 v187, 0x5000, v187
	ds_read_b128 v[76:79], v95 offset:49152
	ds_read_b128 v[80:83], v97 offset:32768
	ds_read_b128 v[84:87], v97 offset:36864
	ds_read_b128 v[88:91], v95 offset:53248
	s_waitcnt lgkmcnt(2)
	v_mfma_f32_32x32x16_bf16 v[34:49], v[80:83], v[76:79], v[34:49]
	global_load_dword v152, v187, s[2:3] nt
	global_load_dword v153, v187, s[2:3] offset:128 nt
	v_add_u32_e32 v187, 0x1000, v187
	global_load_dword v154, v187, s[2:3] nt
	global_load_dword v155, v187, s[2:3] offset:128 nt
	v_add_u32_e32 v187, 0x1000, v187
	s_waitcnt lgkmcnt(1)
	v_mfma_f32_32x32x16_bf16 v[18:33], v[84:87], v[76:79], v[18:33]
	global_load_dword v156, v187, s[2:3] nt
	global_load_dword v157, v187, s[2:3] offset:128 nt
	v_add_u32_e32 v187, 0x1000, v187
	global_load_dword v158, v187, s[2:3] nt
	global_load_dword v159, v187, s[2:3] offset:128 nt
	v_add_u32_e32 v187, 0x5000, v187
	s_waitcnt lgkmcnt(0)
	v_mfma_f32_32x32x16_bf16 v[50:65], v[80:83], v[88:91], v[50:65]
	global_load_dword v160, v187, s[2:3] nt
	global_load_dword v161, v187, s[2:3] offset:128 nt
	v_add_u32_e32 v187, 0x1000, v187
	global_load_dword v162, v187, s[2:3] nt
	global_load_dword v163, v187, s[2:3] offset:128 nt
	v_add_u32_e32 v187, 0x1000, v187
	v_mfma_f32_32x32x16_bf16 v[2:17], v[84:87], v[88:91], v[2:17]
	global_load_dword v164, v187, s[2:3] nt
	global_load_dword v165, v187, s[2:3] offset:128 nt
	v_add_u32_e32 v187, 0x1000, v187
	global_load_dword v166, v187, s[2:3] nt
	global_load_dword v167, v187, s[2:3] offset:128 nt
	v_add_u32_e32 v187, 0x5000, v187
	ds_read_b128 v[76:79], v98 offset:49152
	ds_read_b128 v[80:83], v99 offset:32768
	ds_read_b128 v[84:87], v99 offset:36864
	ds_read_b128 v[88:91], v98 offset:53248
	s_waitcnt lgkmcnt(2)
	v_mfma_f32_32x32x16_bf16 v[34:49], v[80:83], v[76:79], v[34:49]
	global_load_dword v168, v187, s[2:3] nt
	global_load_dword v169, v187, s[2:3] offset:128 nt
	v_add_u32_e32 v187, 0x1000, v187
	global_load_dword v170, v187, s[2:3] nt
	global_load_dword v171, v187, s[2:3] offset:128 nt
	v_add_u32_e32 v187, 0x1000, v187
	s_waitcnt lgkmcnt(1)
	v_mfma_f32_32x32x16_bf16 v[18:33], v[84:87], v[76:79], v[18:33]
	global_load_dword v172, v187, s[2:3] nt
	global_load_dword v173, v187, s[2:3] offset:128 nt
	v_add_u32_e32 v187, 0x1000, v187
	global_load_dword v174, v187, s[2:3] nt
	global_load_dword v175, v187, s[2:3] offset:128 nt
	v_add_u32_e32 v187, 0x5000, v187
	s_waitcnt lgkmcnt(0)
	v_mfma_f32_32x32x16_bf16 v[50:65], v[80:83], v[88:91], v[50:65]
	global_load_dword v176, v187, s[2:3] nt
	global_load_dword v177, v187, s[2:3] offset:128 nt
	v_add_u32_e32 v187, 0x1000, v187
	global_load_dword v178, v187, s[2:3] nt
	global_load_dword v179, v187, s[2:3] offset:128 nt
	v_add_u32_e32 v187, 0x1000, v187
	v_mfma_f32_32x32x16_bf16 v[2:17], v[84:87], v[88:91], v[2:17]
	global_load_dword v180, v187, s[2:3] nt
	global_load_dword v181, v187, s[2:3] offset:128 nt
	v_add_u32_e32 v187, 0x1000, v187
	global_load_dword v182, v187, s[2:3] nt
	global_load_dword v183, v187, s[2:3] offset:128 nt
	ds_read_b128 v[76:79], v100 offset:49152
	ds_read_b128 v[80:83], v101 offset:32768
	ds_read_b128 v[84:87], v101 offset:36864
	ds_read_b128 v[88:91], v100 offset:53248
	s_waitcnt lgkmcnt(0)
	s_barrier
; DI void gemm_out(const Params& p, char* lds) {
;     ...
;         for (int tt = 0; tt < 3; ++tt) {
;             const int row = m0 + wm * 48 + tt * 16 + q;
;             const float* xr = row < NTP ? p.x_p + (size_t)row * DM : p.x_s + (size_t)(row - NTP) * DM;
;             float* o = p.out + (size_t)row * DM;
; #pragma unroll
;             for (int ct = 0; ct < 4; ++ct) { const int col = n0 + wn * 64 + ct * 16 + 4 * g; const float4 xv = xres[tt][ct];
;                 const f32x4 w = {xv.x + acc[ct][tt][0], xv.y + acc[ct][tt][1], xv.z + acc[ct][tt][2], xv.w + acc[ct][tt][3]}; __builtin_nontemporal_store(w, (f32x4*)(o + col)); }
;         }
	v_mfma_f32_32x32x16_bf16 v[34:49], v[80:83], v[76:79], v[34:49]
	v_mfma_f32_32x32x16_bf16 v[18:33], v[84:87], v[76:79], v[18:33]
	v_mfma_f32_32x32x16_bf16 v[50:65], v[80:83], v[88:91], v[50:65]
	v_mfma_f32_32x32x16_bf16 v[2:17], v[84:87], v[88:91], v[2:17]
	s_nop 11
	s_waitcnt vmcnt(63)
	v_add_f32_e32 v34, v34, v120
	global_store_dword v188, v34, s[52:53] nt
	s_waitcnt vmcnt(63)
	v_add_f32_e32 v50, v50, v121
	global_store_dword v188, v50, s[52:53] offset:128 nt
	v_add_u32_e32 v188, 0x1000, v188
	s_waitcnt vmcnt(63)
	v_add_f32_e32 v35, v35, v122
	global_store_dword v188, v35, s[52:53] nt
	s_waitcnt vmcnt(63)
	v_add_f32_e32 v51, v51, v123
	global_store_dword v188, v51, s[52:53] offset:128 nt
	v_add_u32_e32 v188, 0x1000, v188
	s_waitcnt vmcnt(63)
	v_add_f32_e32 v36, v36, v124
	global_store_dword v188, v36, s[52:53] nt
	s_waitcnt vmcnt(63)
	v_add_f32_e32 v52, v52, v125
	global_store_dword v188, v52, s[52:53] offset:128 nt
	v_add_u32_e32 v188, 0x1000, v188
	s_waitcnt vmcnt(63)
	v_add_f32_e32 v37, v37, v126
	global_store_dword v188, v37, s[52:53] nt
	s_waitcnt vmcnt(63)
	v_add_f32_e32 v53, v53, v127
	global_store_dword v188, v53, s[52:53] offset:128 nt
	v_add_u32_e32 v188, 0x5000, v188
	s_waitcnt vmcnt(63)
	v_add_f32_e32 v38, v38, v128
	global_store_dword v188, v38, s[52:53] nt
	s_waitcnt vmcnt(63)
	v_add_f32_e32 v54, v54, v129
	global_store_dword v188, v54, s[52:53] offset:128 nt
	v_add_u32_e32 v188, 0x1000, v188
	s_waitcnt vmcnt(63)
	v_add_f32_e32 v39, v39, v130
	global_store_dword v188, v39, s[52:53] nt
	s_waitcnt vmcnt(63)
	v_add_f32_e32 v55, v55, v131
	global_store_dword v188, v55, s[52:53] offset:128 nt
	v_add_u32_e32 v188, 0x1000, v188
	s_waitcnt vmcnt(63)
	v_add_f32_e32 v40, v40, v132
	global_store_dword v188, v40, s[52:53] nt
	s_waitcnt vmcnt(63)
	v_add_f32_e32 v56, v56, v133
	global_store_dword v188, v56, s[52:53] offset:128 nt
	v_add_u32_e32 v188, 0x1000, v188
	s_waitcnt vmcnt(63)
	v_add_f32_e32 v41, v41, v134
	global_store_dword v188, v41, s[52:53] nt
	s_waitcnt vmcnt(63)
	v_add_f32_e32 v57, v57, v135
	global_store_dword v188, v57, s[52:53] offset:128 nt
	v_add_u32_e32 v188, 0x5000, v188
	s_waitcnt vmcnt(63)
	v_add_f32_e32 v42, v42, v136
	global_store_dword v188, v42, s[52:53] nt
	s_waitcnt vmcnt(63)
	v_add_f32_e32 v58, v58, v137
	global_store_dword v188, v58, s[52:53] offset:128 nt
	v_add_u32_e32 v188, 0x1000, v188
	s_waitcnt vmcnt(63)
	v_add_f32_e32 v43, v43, v138
	global_store_dword v188, v43, s[52:53] nt
	s_waitcnt vmcnt(63)
	v_add_f32_e32 v59, v59, v139
	global_store_dword v188, v59, s[52:53] offset:128 nt
	v_add_u32_e32 v188, 0x1000, v188
	s_waitcnt vmcnt(63)
	v_add_f32_e32 v44, v44, v140
	global_store_dword v188, v44, s[52:53] nt
	s_waitcnt vmcnt(63)
	v_add_f32_e32 v60, v60, v141
	global_store_dword v188, v60, s[52:53] offset:128 nt
	v_add_u32_e32 v188, 0x1000, v188
	s_waitcnt vmcnt(63)
	v_add_f32_e32 v45, v45, v142
	global_store_dword v188, v45, s[52:53] nt
	s_waitcnt vmcnt(63)
	v_add_f32_e32 v61, v61, v143
	global_store_dword v188, v61, s[52:53] offset:128 nt
	v_add_u32_e32 v188, 0x5000, v188
	s_waitcnt vmcnt(63)
	v_add_f32_e32 v46, v46, v144
	global_store_dword v188, v46, s[52:53] nt
	s_waitcnt vmcnt(63)
	v_add_f32_e32 v62, v62, v145
	global_store_dword v188, v62, s[52:53] offset:128 nt
	v_add_u32_e32 v188, 0x1000, v188
	s_waitcnt vmcnt(63)
	v_add_f32_e32 v47, v47, v146
	global_store_dword v188, v47, s[52:53] nt
	s_waitcnt vmcnt(63)
	v_add_f32_e32 v63, v63, v147
	global_store_dword v188, v63, s[52:53] offset:128 nt
	v_add_u32_e32 v188, 0x1000, v188
	s_waitcnt vmcnt(63)
	v_add_f32_e32 v48, v48, v148
	global_store_dword v188, v48, s[52:53] nt
	s_waitcnt vmcnt(63)
	v_add_f32_e32 v64, v64, v149
	global_store_dword v188, v64, s[52:53] offset:128 nt
	v_add_u32_e32 v188, 0x1000, v188
	s_waitcnt vmcnt(63)
	v_add_f32_e32 v49, v49, v150
	global_store_dword v188, v49, s[52:53] nt
	s_waitcnt vmcnt(63)
	v_add_f32_e32 v65, v65, v151
	global_store_dword v188, v65, s[52:53] offset:128 nt
	v_add_u32_e32 v188, 0x5000, v188
	s_waitcnt vmcnt(63)
	v_add_f32_e32 v18, v18, v152
	global_store_dword v188, v18, s[52:53] nt
	s_waitcnt vmcnt(63)
	v_add_f32_e32 v2, v2, v153
	global_store_dword v188, v2, s[52:53] offset:128 nt
	v_add_u32_e32 v188, 0x1000, v188
	s_waitcnt vmcnt(63)
	v_add_f32_e32 v19, v19, v154
	global_store_dword v188, v19, s[52:53] nt
	s_waitcnt vmcnt(63)
	v_add_f32_e32 v3, v3, v155
	global_store_dword v188, v3, s[52:53] offset:128 nt
	v_add_u32_e32 v188, 0x1000, v188
	s_waitcnt vmcnt(63)
	v_add_f32_e32 v20, v20, v156
	global_store_dword v188, v20, s[52:53] nt
	s_waitcnt vmcnt(63)
	v_add_f32_e32 v4, v4, v157
	global_store_dword v188, v4, s[52:53] offset:128 nt
	v_add_u32_e32 v188, 0x1000, v188
	s_waitcnt vmcnt(63)
	v_add_f32_e32 v21, v21, v158
	global_store_dword v188, v21, s[52:53] nt
	s_waitcnt vmcnt(63)
	v_add_f32_e32 v5, v5, v159
	global_store_dword v188, v5, s[52:53] offset:128 nt
	v_add_u32_e32 v188, 0x5000, v188
	s_waitcnt vmcnt(63)
	v_add_f32_e32 v22, v22, v160
	global_store_dword v188, v22, s[52:53] nt
	s_waitcnt vmcnt(63)
	v_add_f32_e32 v6, v6, v161
	global_store_dword v188, v6, s[52:53] offset:128 nt
	v_add_u32_e32 v188, 0x1000, v188
	s_waitcnt vmcnt(63)
	v_add_f32_e32 v23, v23, v162
	global_store_dword v188, v23, s[52:53] nt
	s_waitcnt vmcnt(63)
	v_add_f32_e32 v7, v7, v163
	global_store_dword v188, v7, s[52:53] offset:128 nt
	v_add_u32_e32 v188, 0x1000, v188
	s_waitcnt vmcnt(63)
	v_add_f32_e32 v24, v24, v164
	global_store_dword v188, v24, s[52:53] nt
	s_waitcnt vmcnt(63)
	v_add_f32_e32 v8, v8, v165
	global_store_dword v188, v8, s[52:53] offset:128 nt
	v_add_u32_e32 v188, 0x1000, v188
	s_waitcnt vmcnt(63)
; DI void gemm_out(const Params& p, char* lds) {
;     const u16* __restrict__ A = (const u16*)(p.ws + W_XB); const u16* __restrict__ B = (const u16*)(p.ws + W_WOUTT);
;     const int ntile = 176 * 8;
;     const int vb = (blockIdx.x & 7) * (gridDim.x >> 3) + (blockIdx.x >> 3);
;     for (int tile = vb; tile < ntile; tile += gridDim.x) {
;         int tid = threadIdx.x; asm volatile("" : "+v"(tid));
;         const int lane = tid & 63, wave = __builtin_amdgcn_readfirstlane(tid >> 6); const int wn = wave >> 1, wm = wave & 1; const int q = lane & 15, g = lane >> 4;
;         const int mt = tile >> 3, nt = tile & 7; const int m0 = mt * 96, n0 = nt * 128;
;         f32x4 acc[4][3];
; #pragma unroll
;         for (int a = 0; a < 4; ++a)
; #pragma unroll
;             for (int b = 0; b < 3; ++b) acc[a][b] = (f32x4){0.f, 0.f, 0.f, 0.f};
;         unsigned soffb[4], soffa[3];
; #pragma unroll
;         for (int i = 0; i < 4; ++i) { const int row = 8 * (i * 4 + wave) + (lane >> 3); const int ch = (lane & 7) ^ ((row >> 1) & 7); soffb[i] = (unsigned)(row * 1024 + ch * 8); }
; #pragma unroll
;         for (int i = 0; i < 3; ++i) { const int row = 8 * (i * 4 + wave) + (lane >> 3); const int ch = (lane & 7) ^ ((row >> 1) & 7); soffa[i] = (unsigned)(row * 1024 + ch * 8); }
;         const u16* ga = A + (size_t)m0 * 1024; const u16* gb = B + (size_t)n0 * 1024;
;     ...
;         OSTAGE(0, 0);
;         float4 xres[3][4];
; #pragma unroll
;         for (int tt = 0; tt < 3; ++tt) { const int row = m0 + wm * 48 + tt * 16 + q; const float* xr = row < NTP ? p.x_p + (size_t)row * DM : p.x_s + (size_t)(row - NTP) * DM;
; #pragma unroll
;             for (int ct = 0; ct < 4; ++ct) xres[tt][ct] = ntld4(xr + n0 + wn * 64 + ct * 16 + 4 * g); }
;         __syncthreads();
;     ...
;         for (int tt = 0; tt < 3; ++tt) {
;             const int row = m0 + wm * 48 + tt * 16 + q;
;             const float* xr = row < NTP ? p.x_p + (size_t)row * DM : p.x_s + (size_t)(row - NTP) * DM;
;             float* o = p.out + (size_t)row * DM;
; #pragma unroll
;             for (int ct = 0; ct < 4; ++ct) { const int col = n0 + wn * 64 + ct * 16 + 4 * g; const float4 xv = xres[tt][ct];
;                 const f32x4 w = {xv.x + acc[ct][tt][0], xv.y + acc[ct][tt][1], xv.z + acc[ct][tt][2], xv.w + acc[ct][tt][3]}; __builtin_nontemporal_store(w, (f32x4*)(o + col)); }
;         }
	v_add_f32_e32 v25, v25, v166
	global_store_dword v188, v25, s[52:53] nt
	s_waitcnt vmcnt(63)
	v_add_f32_e32 v9, v9, v167
	global_store_dword v188, v9, s[52:53] offset:128 nt
	v_add_u32_e32 v188, 0x5000, v188
	s_waitcnt vmcnt(63)
	v_add_f32_e32 v26, v26, v168
	global_store_dword v188, v26, s[52:53] nt
	s_waitcnt vmcnt(63)
	v_add_f32_e32 v10, v10, v169
	global_store_dword v188, v10, s[52:53] offset:128 nt
	v_add_u32_e32 v188, 0x1000, v188
	s_waitcnt vmcnt(63)
	v_add_f32_e32 v27, v27, v170
	global_store_dword v188, v27, s[52:53] nt
	s_waitcnt vmcnt(63)
	v_add_f32_e32 v11, v11, v171
	global_store_dword v188, v11, s[52:53] offset:128 nt
	v_add_u32_e32 v188, 0x1000, v188
	s_waitcnt vmcnt(63)
	v_add_f32_e32 v28, v28, v172
	global_store_dword v188, v28, s[52:53] nt
	s_waitcnt vmcnt(63)
	v_add_f32_e32 v12, v12, v173
	global_store_dword v188, v12, s[52:53] offset:128 nt
	v_add_u32_e32 v188, 0x1000, v188
	s_waitcnt vmcnt(63)
	v_add_f32_e32 v29, v29, v174
	global_store_dword v188, v29, s[52:53] nt
	s_waitcnt vmcnt(63)
	v_add_f32_e32 v13, v13, v175
	global_store_dword v188, v13, s[52:53] offset:128 nt
	v_add_u32_e32 v188, 0x5000, v188
	s_waitcnt vmcnt(63)
	v_add_f32_e32 v30, v30, v176
	global_store_dword v188, v30, s[52:53] nt
	s_waitcnt vmcnt(63)
	v_add_f32_e32 v14, v14, v177
	global_store_dword v188, v14, s[52:53] offset:128 nt
	v_add_u32_e32 v188, 0x1000, v188
	s_waitcnt vmcnt(63)
	v_add_f32_e32 v31, v31, v178
	global_store_dword v188, v31, s[52:53] nt
	s_waitcnt vmcnt(63)
	v_add_f32_e32 v15, v15, v179
	global_store_dword v188, v15, s[52:53] offset:128 nt
	v_add_u32_e32 v188, 0x1000, v188
	s_waitcnt vmcnt(63)
	v_add_f32_e32 v32, v32, v180
	global_store_dword v188, v32, s[52:53] nt
	s_waitcnt vmcnt(63)
	v_add_f32_e32 v16, v16, v181
	global_store_dword v188, v16, s[52:53] offset:128 nt
	v_add_u32_e32 v188, 0x1000, v188
	s_waitcnt vmcnt(63)
	v_add_f32_e32 v33, v33, v182
	global_store_dword v188, v33, s[52:53] nt
	s_waitcnt vmcnt(63)
	v_add_f32_e32 v17, v17, v183
	global_store_dword v188, v17, s[52:53] offset:128 nt
	v_readlane_b32 s95, v236, 8
	s_cmpk_lt_i32 s33, 0x400
	s_mov_b32 s0, s88
	s_mov_b32 s82, s86
	s_cbranch_scc1 .Lo_tile
	s_cmp_gt_u32 s64, 0x7f
	s_cbranch_scc1 .LBB0_578
	s_lshr_b32 s4, s64, 4
	s_lshl_b32 s4, s4, 6
	s_add_i32 s4, s4, 0x4000
	s_and_b32 s5, s64, 15
	s_lshl_b32 s5, s5, 6
	v_readfirstlane_b32 s6, v0
	s_lshr_b32 s6, s6, 6
	s_and_b32 s7, s6, 1
	s_lshr_b32 s8, s6, 1
	s_lshl_b32 s1, s6, 10
	s_lshl_b32 s9, s7, 5
	s_add_i32 s9, s9, s4
	s_lshl_b32 s20, s8, 5
	s_add_i32 s20, s20, s5
	v_and_b32_e32 v24, 31, v0
	v_bfe_u32 v21, v0, 5, 1
	v_add_u32_e32 v23, s20, v24
	v_lshlrev_b32_e32 v34, 14, v21
	v_lshl_add_u32 v34, v23, 2, v34
	s_lshl_b32 s21, s9, 12
	s_sub_i32 s22, s9, 0x4000
	s_lshl_b32 s22, s22, 12
	v_add_u32_e32 v35, s21, v34
	v_add_u32_e32 v34, s22, v34
	global_load_dword v40, v34, s[58:59] nt
	v_add_u32_e32 v34, 0x1000, v34
	global_load_dword v41, v34, s[58:59] nt
	v_add_u32_e32 v34, 0x1000, v34
	global_load_dword v42, v34, s[58:59] nt
	v_add_u32_e32 v34, 0x1000, v34
	global_load_dword v43, v34, s[58:59] nt
	v_add_u32_e32 v34, 0x5000, v34
	global_load_dword v44, v34, s[58:59] nt
	v_add_u32_e32 v34, 0x1000, v34
	global_load_dword v45, v34, s[58:59] nt
	v_add_u32_e32 v34, 0x1000, v34
	global_load_dword v46, v34, s[58:59] nt
	v_add_u32_e32 v34, 0x1000, v34
	global_load_dword v47, v34, s[58:59] nt
	v_add_u32_e32 v34, 0x5000, v34
	global_load_dword v48, v34, s[58:59] nt
	v_add_u32_e32 v34, 0x1000, v34
	global_load_dword v49, v34, s[58:59] nt
	v_add_u32_e32 v34, 0x1000, v34
	global_load_dword v50, v34, s[58:59] nt
	v_add_u32_e32 v34, 0x1000, v34
	global_load_dword v51, v34, s[58:59] nt
	v_add_u32_e32 v34, 0x5000, v34
	global_load_dword v52, v34, s[58:59] nt
	v_add_u32_e32 v34, 0x1000, v34
	global_load_dword v53, v34, s[58:59] nt
	v_add_u32_e32 v34, 0x1000, v34
	global_load_dword v54, v34, s[58:59] nt
	v_add_u32_e32 v34, 0x1000, v34
	global_load_dword v55, v34, s[58:59] nt
	v_bfe_u32 v2, v0, 3, 3
	v_lshl_or_b32 v2, s6, 3, v2
	v_lshrrev_b32_e32 v3, 1, v2
	v_xor_b32_e32 v3, v3, v0
	v_lshlrev_b32_e32 v3, 4, v3
	v_and_b32_e32 v3, 0x70, v3
	v_lshl_or_b32 v6, v2, 11, v3
	v_mov_b32_e32 v7, 0
	s_lshl_b32 s9, s4, 11
	s_add_u32 s10, s54, s9
	s_addc_u32 s11, s55, 0
	s_lshl_b32 s9, s5, 11
	s_add_u32 s12, s54, 0x2940000
	s_addc_u32 s13, s55, 0
	s_add_u32 s12, s12, s9
	s_addc_u32 s13, s13, 0
	s_mov_b64 s[14:15], 0x10000
	s_mov_b64 s[16:17], 0x80
	v_lshl_add_u64 v[10:11], s[10:11], 0, v[6:7]
	v_lshl_add_u64 v[14:15], s[12:13], 0, v[6:7]
	v_lshl_add_u64 v[12:13], v[10:11], 0, s[14:15]
	v_lshl_add_u64 v[16:17], v[14:15], 0, s[14:15]
	v_bfe_u32 v20, v0, 1, 3
	v_xor_b32_e32 v22, v21, v20
	v_lshlrev_b32_e32 v24, 7, v24
	s_lshl_b32 s18, s7, 12
	s_lshl_b32 s19, s8, 12
	s_add_i32 s19, s19, 0x2000
	v_lshl_add_u32 v23, v22, 4, v24
	v_add_u32_e32 v26, s18, v23
	v_add_u32_e32 v30, s19, v23
	v_xor_b32_e32 v23, 2, v22
	v_lshl_add_u32 v23, v23, 4, v24
	v_add_u32_e32 v27, s18, v23
	v_add_u32_e32 v31, s19, v23
	v_xor_b32_e32 v23, 4, v22
	v_lshl_add_u32 v23, v23, 4, v24
	v_add_u32_e32 v28, s18, v23
	v_add_u32_e32 v32, s19, v23
	v_xor_b32_e32 v23, 6, v22
	v_lshl_add_u32 v23, v23, 4, v24
	v_add_u32_e32 v29, s18, v23
	v_add_u32_e32 v33, s19, v23
	s_add_i32 m0, s1, 0x0
	s_nop 0
	global_load_lds_dwordx4 v[10:11], off sc1
	s_add_i32 m0, s1, 0x1000
	v_lshl_add_u64 v[10:11], v[10:11], 0, s[16:17]
	global_load_lds_dwordx4 v[12:13], off sc1
	s_add_i32 m0, s1, 0x2000
	v_lshl_add_u64 v[12:13], v[12:13], 0, s[16:17]
	global_load_lds_dwordx4 v[14:15], off
	s_add_i32 m0, s1, 0x3000
	v_lshl_add_u64 v[14:15], v[14:15], 0, s[16:17]
	global_load_lds_dwordx4 v[16:17], off
	v_lshl_add_u64 v[16:17], v[16:17], 0, s[16:17]
	s_add_i32 m0, s1, 0x4000
	s_nop 0
	global_load_lds_dwordx4 v[10:11], off sc1
	s_add_i32 m0, s1, 0x5000
	v_lshl_add_u64 v[10:11], v[10:11], 0, s[16:17]
	global_load_lds_dwordx4 v[12:13], off sc1
	s_add_i32 m0, s1, 0x6000
	v_lshl_add_u64 v[12:13], v[12:13], 0, s[16:17]
	global_load_lds_dwordx4 v[14:15], off
	s_add_i32 m0, s1, 0x7000
	v_lshl_add_u64 v[14:15], v[14:15], 0, s[16:17]
	global_load_lds_dwordx4 v[16:17], off
	v_lshl_add_u64 v[16:17], v[16:17], 0, s[16:17]
	s_add_i32 m0, s1, 0x8000
	s_nop 0
	global_load_lds_dwordx4 v[10:11], off sc1
	s_add_i32 m0, s1, 0x9000
	v_lshl_add_u64 v[10:11], v[10:11], 0, s[16:17]
	global_load_lds_dwordx4 v[12:13], off sc1
	s_add_i32 m0, s1, 0xa000
	v_lshl_add_u64 v[12:13], v[12:13], 0, s[16:17]
	global_load_lds_dwordx4 v[14:15], off
	s_add_i32 m0, s1, 0xb000
	v_lshl_add_u64 v[14:15], v[14:15], 0, s[16:17]
	global_load_lds_dwordx4 v[16:17], off
	v_lshl_add_u64 v[16:17], v[16:17], 0, s[16:17]
	s_waitcnt vmcnt(8)
	s_barrier
; DI void gemm_out(const Params& p, char* lds) {
;     ...
;         for (int kt = 0; kt < 16; ++kt) {
;             if (kt + 1 < 16) OSTAGE((kt + 1) & 1, kt + 1);
;             const char* sb = lds + (kt & 1) * 28672; const char* sa = sb + 16384;
; #pragma unroll
;             for (int ks = 0; ks < 2; ++ks) {
;                 bf16x8 fw[4], fx[3];
; #pragma unroll
;                 for (int ct = 0; ct < 4; ++ct) fw[ct] = *(const bf16x8*)(sb + swz(wn * 64 + ct * 16 + q, 4 * ks + g));
; #pragma unroll
;                 for (int tt = 0; tt < 3; ++tt) fx[tt] = *(const bf16x8*)(sa + swz(wm * 48 + tt * 16 + q, 4 * ks + g));
; #pragma unroll
;                 for (int ct = 0; ct < 4; ++ct)
; #pragma unroll
;                     for (int tt = 0; tt < 3; ++tt) acc[ct][tt] = __builtin_amdgcn_mfma_f32_16x16x32_bf16(fw[ct], fx[tt], acc[ct][tt], 0, 0, 0);
;             }
;             __syncthreads();
;         }
	s_add_i32 m0, s1, 0xc000
	s_nop 0
	global_load_lds_dwordx4 v[10:11], off sc1
	s_add_i32 m0, s1, 0xd000
	v_lshl_add_u64 v[10:11], v[10:11], 0, s[16:17]
	global_load_lds_dwordx4 v[12:13], off sc1
	s_add_i32 m0, s1, 0xe000
	v_lshl_add_u64 v[12:13], v[12:13], 0, s[16:17]
	global_load_lds_dwordx4 v[14:15], off
	s_add_i32 m0, s1, 0xf000
	v_lshl_add_u64 v[14:15], v[14:15], 0, s[16:17]
	global_load_lds_dwordx4 v[16:17], off
	v_lshl_add_u64 v[16:17], v[16:17], 0, s[16:17]
	ds_read_b128 v[80:83], v26 offset:0
	ds_read_b128 v[96:99], v30 offset:0
	ds_read_b128 v[84:87], v27 offset:0
	ds_read_b128 v[100:103], v31 offset:0
	ds_read_b128 v[88:91], v28 offset:0
	ds_read_b128 v[104:107], v32 offset:0
	ds_read_b128 v[92:95], v29 offset:0
	ds_read_b128 v[108:111], v33 offset:0
	s_waitcnt lgkmcnt(6)
	v_mfma_f32_32x32x16_bf16 v[64:79], v[80:83], v[96:99], 0
	s_waitcnt lgkmcnt(4)
	v_mfma_f32_32x32x16_bf16 v[64:79], v[84:87], v[100:103], v[64:79]
	s_waitcnt lgkmcnt(2)
	v_mfma_f32_32x32x16_bf16 v[64:79], v[88:91], v[104:107], v[64:79]
	s_waitcnt lgkmcnt(0)
	v_mfma_f32_32x32x16_bf16 v[64:79], v[92:95], v[108:111], v[64:79]
	s_waitcnt vmcnt(8)
	s_barrier
	s_add_i32 m0, s1, 0x0
	s_nop 0
	global_load_lds_dwordx4 v[10:11], off sc1
	s_add_i32 m0, s1, 0x1000
	v_lshl_add_u64 v[10:11], v[10:11], 0, s[16:17]
	global_load_lds_dwordx4 v[12:13], off sc1
	s_add_i32 m0, s1, 0x2000
	v_lshl_add_u64 v[12:13], v[12:13], 0, s[16:17]
	global_load_lds_dwordx4 v[14:15], off
	s_add_i32 m0, s1, 0x3000
	v_lshl_add_u64 v[14:15], v[14:15], 0, s[16:17]
	global_load_lds_dwordx4 v[16:17], off
	v_lshl_add_u64 v[16:17], v[16:17], 0, s[16:17]
	ds_read_b128 v[80:83], v26 offset:16384
	ds_read_b128 v[96:99], v30 offset:16384
	ds_read_b128 v[84:87], v27 offset:16384
	ds_read_b128 v[100:103], v31 offset:16384
	ds_read_b128 v[88:91], v28 offset:16384
	ds_read_b128 v[104:107], v32 offset:16384
	ds_read_b128 v[92:95], v29 offset:16384
	ds_read_b128 v[108:111], v33 offset:16384
	s_waitcnt lgkmcnt(6)
	v_mfma_f32_32x32x16_bf16 v[64:79], v[80:83], v[96:99], v[64:79]
	s_waitcnt lgkmcnt(4)
	v_mfma_f32_32x32x16_bf16 v[64:79], v[84:87], v[100:103], v[64:79]
	s_waitcnt lgkmcnt(2)
	v_mfma_f32_32x32x16_bf16 v[64:79], v[88:91], v[104:107], v[64:79]
	s_waitcnt lgkmcnt(0)
	v_mfma_f32_32x32x16_bf16 v[64:79], v[92:95], v[108:111], v[64:79]
	s_waitcnt vmcnt(8)
	s_barrier
	s_add_i32 m0, s1, 0x4000
	s_nop 0
	global_load_lds_dwordx4 v[10:11], off sc1
	s_add_i32 m0, s1, 0x5000
	v_lshl_add_u64 v[10:11], v[10:11], 0, s[16:17]
	global_load_lds_dwordx4 v[12:13], off sc1
	s_add_i32 m0, s1, 0x6000
	v_lshl_add_u64 v[12:13], v[12:13], 0, s[16:17]
	global_load_lds_dwordx4 v[14:15], off
	s_add_i32 m0, s1, 0x7000
	v_lshl_add_u64 v[14:15], v[14:15], 0, s[16:17]
	global_load_lds_dwordx4 v[16:17], off
	v_lshl_add_u64 v[16:17], v[16:17], 0, s[16:17]
	ds_read_b128 v[80:83], v26 offset:32768
	ds_read_b128 v[96:99], v30 offset:32768
	ds_read_b128 v[84:87], v27 offset:32768
	ds_read_b128 v[100:103], v31 offset:32768
	ds_read_b128 v[88:91], v28 offset:32768
	ds_read_b128 v[104:107], v32 offset:32768
	ds_read_b128 v[92:95], v29 offset:32768
	ds_read_b128 v[108:111], v33 offset:32768
	s_waitcnt lgkmcnt(6)
	v_mfma_f32_32x32x16_bf16 v[64:79], v[80:83], v[96:99], v[64:79]
	s_waitcnt lgkmcnt(4)
	v_mfma_f32_32x32x16_bf16 v[64:79], v[84:87], v[100:103], v[64:79]
	s_waitcnt lgkmcnt(2)
	v_mfma_f32_32x32x16_bf16 v[64:79], v[88:91], v[104:107], v[64:79]
	s_waitcnt lgkmcnt(0)
	v_mfma_f32_32x32x16_bf16 v[64:79], v[92:95], v[108:111], v[64:79]
	s_waitcnt vmcnt(8)
	s_barrier
	s_add_i32 m0, s1, 0x8000
	s_nop 0
	global_load_lds_dwordx4 v[10:11], off sc1
	s_add_i32 m0, s1, 0x9000
	v_lshl_add_u64 v[10:11], v[10:11], 0, s[16:17]
	global_load_lds_dwordx4 v[12:13], off sc1
	s_add_i32 m0, s1, 0xa000
	v_lshl_add_u64 v[12:13], v[12:13], 0, s[16:17]
	global_load_lds_dwordx4 v[14:15], off
	s_add_i32 m0, s1, 0xb000
	v_lshl_add_u64 v[14:15], v[14:15], 0, s[16:17]
	global_load_lds_dwordx4 v[16:17], off
	v_lshl_add_u64 v[16:17], v[16:17], 0, s[16:17]
	ds_read_b128 v[80:83], v26 offset:49152
	ds_read_b128 v[96:99], v30 offset:49152
	ds_read_b128 v[84:87], v27 offset:49152
	ds_read_b128 v[100:103], v31 offset:49152
	ds_read_b128 v[88:91], v28 offset:49152
	ds_read_b128 v[104:107], v32 offset:49152
	ds_read_b128 v[92:95], v29 offset:49152
	ds_read_b128 v[108:111], v33 offset:49152
	s_waitcnt lgkmcnt(6)
	v_mfma_f32_32x32x16_bf16 v[64:79], v[80:83], v[96:99], v[64:79]
	s_waitcnt lgkmcnt(4)
	v_mfma_f32_32x32x16_bf16 v[64:79], v[84:87], v[100:103], v[64:79]
	s_waitcnt lgkmcnt(2)
	v_mfma_f32_32x32x16_bf16 v[64:79], v[88:91], v[104:107], v[64:79]
	s_waitcnt lgkmcnt(0)
	v_mfma_f32_32x32x16_bf16 v[64:79], v[92:95], v[108:111], v[64:79]
	s_waitcnt vmcnt(8)
	s_barrier
	s_add_i32 m0, s1, 0xc000
	s_nop 0
	global_load_lds_dwordx4 v[10:11], off sc1
	s_add_i32 m0, s1, 0xd000
	v_lshl_add_u64 v[10:11], v[10:11], 0, s[16:17]
	global_load_lds_dwordx4 v[12:13], off sc1
	s_add_i32 m0, s1, 0xe000
	v_lshl_add_u64 v[12:13], v[12:13], 0, s[16:17]
	global_load_lds_dwordx4 v[14:15], off
	s_add_i32 m0, s1, 0xf000
	v_lshl_add_u64 v[14:15], v[14:15], 0, s[16:17]
	global_load_lds_dwordx4 v[16:17], off
	v_lshl_add_u64 v[16:17], v[16:17], 0, s[16:17]
	ds_read_b128 v[80:83], v26 offset:0
	ds_read_b128 v[96:99], v30 offset:0
	ds_read_b128 v[84:87], v27 offset:0
	ds_read_b128 v[100:103], v31 offset:0
	ds_read_b128 v[88:91], v28 offset:0
	ds_read_b128 v[104:107], v32 offset:0
	ds_read_b128 v[92:95], v29 offset:0
	ds_read_b128 v[108:111], v33 offset:0
	s_waitcnt lgkmcnt(6)
	v_mfma_f32_32x32x16_bf16 v[64:79], v[80:83], v[96:99], v[64:79]
	s_waitcnt lgkmcnt(4)
	v_mfma_f32_32x32x16_bf16 v[64:79], v[84:87], v[100:103], v[64:79]
	s_waitcnt lgkmcnt(2)
	v_mfma_f32_32x32x16_bf16 v[64:79], v[88:91], v[104:107], v[64:79]
	s_waitcnt lgkmcnt(0)
	v_mfma_f32_32x32x16_bf16 v[64:79], v[92:95], v[108:111], v[64:79]
	s_waitcnt vmcnt(8)
	s_barrier
; DI void gemm_out(const Params& p, char* lds) {
;     ...
;         for (int kt = 0; kt < 16; ++kt) {
;             if (kt + 1 < 16) OSTAGE((kt + 1) & 1, kt + 1);
;             const char* sb = lds + (kt & 1) * 28672; const char* sa = sb + 16384;
; #pragma unroll
;             for (int ks = 0; ks < 2; ++ks) {
;                 bf16x8 fw[4], fx[3];
; #pragma unroll
;                 for (int ct = 0; ct < 4; ++ct) fw[ct] = *(const bf16x8*)(sb + swz(wn * 64 + ct * 16 + q, 4 * ks + g));
; #pragma unroll
;                 for (int tt = 0; tt < 3; ++tt) fx[tt] = *(const bf16x8*)(sa + swz(wm * 48 + tt * 16 + q, 4 * ks + g));
; #pragma unroll
;                 for (int ct = 0; ct < 4; ++ct)
; #pragma unroll
;                     for (int tt = 0; tt < 3; ++tt) acc[ct][tt] = __builtin_amdgcn_mfma_f32_16x16x32_bf16(fw[ct], fx[tt], acc[ct][tt], 0, 0, 0);
;             }
;             __syncthreads();
;         }
	s_add_i32 m0, s1, 0x0
	s_nop 0
	global_load_lds_dwordx4 v[10:11], off sc1
	s_add_i32 m0, s1, 0x1000
	v_lshl_add_u64 v[10:11], v[10:11], 0, s[16:17]
	global_load_lds_dwordx4 v[12:13], off sc1
	s_add_i32 m0, s1, 0x2000
	v_lshl_add_u64 v[12:13], v[12:13], 0, s[16:17]
	global_load_lds_dwordx4 v[14:15], off
	s_add_i32 m0, s1, 0x3000
	v_lshl_add_u64 v[14:15], v[14:15], 0, s[16:17]
	global_load_lds_dwordx4 v[16:17], off
	v_lshl_add_u64 v[16:17], v[16:17], 0, s[16:17]
	ds_read_b128 v[80:83], v26 offset:16384
	ds_read_b128 v[96:99], v30 offset:16384
	ds_read_b128 v[84:87], v27 offset:16384
	ds_read_b128 v[100:103], v31 offset:16384
	ds_read_b128 v[88:91], v28 offset:16384
	ds_read_b128 v[104:107], v32 offset:16384
	ds_read_b128 v[92:95], v29 offset:16384
	ds_read_b128 v[108:111], v33 offset:16384
	s_waitcnt lgkmcnt(6)
	v_mfma_f32_32x32x16_bf16 v[64:79], v[80:83], v[96:99], v[64:79]
	s_waitcnt lgkmcnt(4)
	v_mfma_f32_32x32x16_bf16 v[64:79], v[84:87], v[100:103], v[64:79]
	s_waitcnt lgkmcnt(2)
	v_mfma_f32_32x32x16_bf16 v[64:79], v[88:91], v[104:107], v[64:79]
	s_waitcnt lgkmcnt(0)
	v_mfma_f32_32x32x16_bf16 v[64:79], v[92:95], v[108:111], v[64:79]
	s_waitcnt vmcnt(8)
	s_barrier
	s_add_i32 m0, s1, 0x4000
	s_nop 0
	global_load_lds_dwordx4 v[10:11], off sc1
	s_add_i32 m0, s1, 0x5000
	v_lshl_add_u64 v[10:11], v[10:11], 0, s[16:17]
	global_load_lds_dwordx4 v[12:13], off sc1
	s_add_i32 m0, s1, 0x6000
	v_lshl_add_u64 v[12:13], v[12:13], 0, s[16:17]
	global_load_lds_dwordx4 v[14:15], off
	s_add_i32 m0, s1, 0x7000
	v_lshl_add_u64 v[14:15], v[14:15], 0, s[16:17]
	global_load_lds_dwordx4 v[16:17], off
	v_lshl_add_u64 v[16:17], v[16:17], 0, s[16:17]
	ds_read_b128 v[80:83], v26 offset:32768
	ds_read_b128 v[96:99], v30 offset:32768
	ds_read_b128 v[84:87], v27 offset:32768
	ds_read_b128 v[100:103], v31 offset:32768
	ds_read_b128 v[88:91], v28 offset:32768
	ds_read_b128 v[104:107], v32 offset:32768
	ds_read_b128 v[92:95], v29 offset:32768
	ds_read_b128 v[108:111], v33 offset:32768
	s_waitcnt lgkmcnt(6)
	v_mfma_f32_32x32x16_bf16 v[64:79], v[80:83], v[96:99], v[64:79]
	s_waitcnt lgkmcnt(4)
	v_mfma_f32_32x32x16_bf16 v[64:79], v[84:87], v[100:103], v[64:79]
	s_waitcnt lgkmcnt(2)
	v_mfma_f32_32x32x16_bf16 v[64:79], v[88:91], v[104:107], v[64:79]
	s_waitcnt lgkmcnt(0)
	v_mfma_f32_32x32x16_bf16 v[64:79], v[92:95], v[108:111], v[64:79]
	s_waitcnt vmcnt(8)
	s_barrier
	s_add_i32 m0, s1, 0x8000
	s_nop 0
	global_load_lds_dwordx4 v[10:11], off sc1
	s_add_i32 m0, s1, 0x9000
	v_lshl_add_u64 v[10:11], v[10:11], 0, s[16:17]
	global_load_lds_dwordx4 v[12:13], off sc1
	s_add_i32 m0, s1, 0xa000
	v_lshl_add_u64 v[12:13], v[12:13], 0, s[16:17]
	global_load_lds_dwordx4 v[14:15], off
	s_add_i32 m0, s1, 0xb000
	v_lshl_add_u64 v[14:15], v[14:15], 0, s[16:17]
	global_load_lds_dwordx4 v[16:17], off
	v_lshl_add_u64 v[16:17], v[16:17], 0, s[16:17]
	ds_read_b128 v[80:83], v26 offset:49152
	ds_read_b128 v[96:99], v30 offset:49152
	ds_read_b128 v[84:87], v27 offset:49152
	ds_read_b128 v[100:103], v31 offset:49152
	ds_read_b128 v[88:91], v28 offset:49152
	ds_read_b128 v[104:107], v32 offset:49152
	ds_read_b128 v[92:95], v29 offset:49152
	ds_read_b128 v[108:111], v33 offset:49152
	s_waitcnt lgkmcnt(6)
	v_mfma_f32_32x32x16_bf16 v[64:79], v[80:83], v[96:99], v[64:79]
	s_waitcnt lgkmcnt(4)
	v_mfma_f32_32x32x16_bf16 v[64:79], v[84:87], v[100:103], v[64:79]
	s_waitcnt lgkmcnt(2)
	v_mfma_f32_32x32x16_bf16 v[64:79], v[88:91], v[104:107], v[64:79]
	s_waitcnt lgkmcnt(0)
	v_mfma_f32_32x32x16_bf16 v[64:79], v[92:95], v[108:111], v[64:79]
	s_waitcnt vmcnt(8)
	s_barrier
	s_add_i32 m0, s1, 0xc000
	s_nop 0
	global_load_lds_dwordx4 v[10:11], off sc1
	s_add_i32 m0, s1, 0xd000
	v_lshl_add_u64 v[10:11], v[10:11], 0, s[16:17]
	global_load_lds_dwordx4 v[12:13], off sc1
	s_add_i32 m0, s1, 0xe000
	v_lshl_add_u64 v[12:13], v[12:13], 0, s[16:17]
	global_load_lds_dwordx4 v[14:15], off
	s_add_i32 m0, s1, 0xf000
	v_lshl_add_u64 v[14:15], v[14:15], 0, s[16:17]
	global_load_lds_dwordx4 v[16:17], off
	v_lshl_add_u64 v[16:17], v[16:17], 0, s[16:17]
	ds_read_b128 v[80:83], v26 offset:0
	ds_read_b128 v[96:99], v30 offset:0
	ds_read_b128 v[84:87], v27 offset:0
	ds_read_b128 v[100:103], v31 offset:0
	ds_read_b128 v[88:91], v28 offset:0
	ds_read_b128 v[104:107], v32 offset:0
	ds_read_b128 v[92:95], v29 offset:0
	ds_read_b128 v[108:111], v33 offset:0
	s_waitcnt lgkmcnt(6)
	v_mfma_f32_32x32x16_bf16 v[64:79], v[80:83], v[96:99], v[64:79]
	s_waitcnt lgkmcnt(4)
	v_mfma_f32_32x32x16_bf16 v[64:79], v[84:87], v[100:103], v[64:79]
	s_waitcnt lgkmcnt(2)
	v_mfma_f32_32x32x16_bf16 v[64:79], v[88:91], v[104:107], v[64:79]
	s_waitcnt lgkmcnt(0)
	v_mfma_f32_32x32x16_bf16 v[64:79], v[92:95], v[108:111], v[64:79]
	s_waitcnt vmcnt(8)
	s_barrier
	s_add_i32 m0, s1, 0x0
	s_nop 0
	global_load_lds_dwordx4 v[10:11], off sc1
	s_add_i32 m0, s1, 0x1000
	v_lshl_add_u64 v[10:11], v[10:11], 0, s[16:17]
	global_load_lds_dwordx4 v[12:13], off sc1
	s_add_i32 m0, s1, 0x2000
	v_lshl_add_u64 v[12:13], v[12:13], 0, s[16:17]
	global_load_lds_dwordx4 v[14:15], off
	s_add_i32 m0, s1, 0x3000
	v_lshl_add_u64 v[14:15], v[14:15], 0, s[16:17]
	global_load_lds_dwordx4 v[16:17], off
	v_lshl_add_u64 v[16:17], v[16:17], 0, s[16:17]
	ds_read_b128 v[80:83], v26 offset:16384
	ds_read_b128 v[96:99], v30 offset:16384
	ds_read_b128 v[84:87], v27 offset:16384
	ds_read_b128 v[100:103], v31 offset:16384
	ds_read_b128 v[88:91], v28 offset:16384
	ds_read_b128 v[104:107], v32 offset:16384
	ds_read_b128 v[92:95], v29 offset:16384
	ds_read_b128 v[108:111], v33 offset:16384
	s_waitcnt lgkmcnt(6)
	v_mfma_f32_32x32x16_bf16 v[64:79], v[80:83], v[96:99], v[64:79]
	s_waitcnt lgkmcnt(4)
	v_mfma_f32_32x32x16_bf16 v[64:79], v[84:87], v[100:103], v[64:79]
	s_waitcnt lgkmcnt(2)
	v_mfma_f32_32x32x16_bf16 v[64:79], v[88:91], v[104:107], v[64:79]
	s_waitcnt lgkmcnt(0)
	v_mfma_f32_32x32x16_bf16 v[64:79], v[92:95], v[108:111], v[64:79]
	s_waitcnt vmcnt(8)
	s_barrier
; DI void gemm_out(const Params& p, char* lds) {
;     ...
;         for (int kt = 0; kt < 16; ++kt) {
;             if (kt + 1 < 16) OSTAGE((kt + 1) & 1, kt + 1);
;             const char* sb = lds + (kt & 1) * 28672; const char* sa = sb + 16384;
; #pragma unroll
;             for (int ks = 0; ks < 2; ++ks) {
;                 bf16x8 fw[4], fx[3];
; #pragma unroll
;                 for (int ct = 0; ct < 4; ++ct) fw[ct] = *(const bf16x8*)(sb + swz(wn * 64 + ct * 16 + q, 4 * ks + g));
; #pragma unroll
;                 for (int tt = 0; tt < 3; ++tt) fx[tt] = *(const bf16x8*)(sa + swz(wm * 48 + tt * 16 + q, 4 * ks + g));
; #pragma unroll
;                 for (int ct = 0; ct < 4; ++ct)
; #pragma unroll
;                     for (int tt = 0; tt < 3; ++tt) acc[ct][tt] = __builtin_amdgcn_mfma_f32_16x16x32_bf16(fw[ct], fx[tt], acc[ct][tt], 0, 0, 0);
;             }
;             __syncthreads();
;         }
	s_add_i32 m0, s1, 0x4000
	s_nop 0
	global_load_lds_dwordx4 v[10:11], off sc1
	s_add_i32 m0, s1, 0x5000
	v_lshl_add_u64 v[10:11], v[10:11], 0, s[16:17]
	global_load_lds_dwordx4 v[12:13], off sc1
	s_add_i32 m0, s1, 0x6000
	v_lshl_add_u64 v[12:13], v[12:13], 0, s[16:17]
	global_load_lds_dwordx4 v[14:15], off
	s_add_i32 m0, s1, 0x7000
	v_lshl_add_u64 v[14:15], v[14:15], 0, s[16:17]
	global_load_lds_dwordx4 v[16:17], off
	v_lshl_add_u64 v[16:17], v[16:17], 0, s[16:17]
	ds_read_b128 v[80:83], v26 offset:32768
	ds_read_b128 v[96:99], v30 offset:32768
	ds_read_b128 v[84:87], v27 offset:32768
	ds_read_b128 v[100:103], v31 offset:32768
	ds_read_b128 v[88:91], v28 offset:32768
	ds_read_b128 v[104:107], v32 offset:32768
	ds_read_b128 v[92:95], v29 offset:32768
	ds_read_b128 v[108:111], v33 offset:32768
	s_waitcnt lgkmcnt(6)
	v_mfma_f32_32x32x16_bf16 v[64:79], v[80:83], v[96:99], v[64:79]
	s_waitcnt lgkmcnt(4)
	v_mfma_f32_32x32x16_bf16 v[64:79], v[84:87], v[100:103], v[64:79]
	s_waitcnt lgkmcnt(2)
	v_mfma_f32_32x32x16_bf16 v[64:79], v[88:91], v[104:107], v[64:79]
	s_waitcnt lgkmcnt(0)
	v_mfma_f32_32x32x16_bf16 v[64:79], v[92:95], v[108:111], v[64:79]
	s_waitcnt vmcnt(8)
	s_barrier
	s_add_i32 m0, s1, 0x8000
	s_nop 0
	global_load_lds_dwordx4 v[10:11], off sc1
	s_add_i32 m0, s1, 0x9000
	v_lshl_add_u64 v[10:11], v[10:11], 0, s[16:17]
	global_load_lds_dwordx4 v[12:13], off sc1
	s_add_i32 m0, s1, 0xa000
	v_lshl_add_u64 v[12:13], v[12:13], 0, s[16:17]
	global_load_lds_dwordx4 v[14:15], off
	s_add_i32 m0, s1, 0xb000
	v_lshl_add_u64 v[14:15], v[14:15], 0, s[16:17]
	global_load_lds_dwordx4 v[16:17], off
	v_lshl_add_u64 v[16:17], v[16:17], 0, s[16:17]
	ds_read_b128 v[80:83], v26 offset:49152
	ds_read_b128 v[96:99], v30 offset:49152
	ds_read_b128 v[84:87], v27 offset:49152
	ds_read_b128 v[100:103], v31 offset:49152
	ds_read_b128 v[88:91], v28 offset:49152
	ds_read_b128 v[104:107], v32 offset:49152
	ds_read_b128 v[92:95], v29 offset:49152
	ds_read_b128 v[108:111], v33 offset:49152
	s_waitcnt lgkmcnt(6)
	v_mfma_f32_32x32x16_bf16 v[64:79], v[80:83], v[96:99], v[64:79]
	s_waitcnt lgkmcnt(4)
	v_mfma_f32_32x32x16_bf16 v[64:79], v[84:87], v[100:103], v[64:79]
	s_waitcnt lgkmcnt(2)
	v_mfma_f32_32x32x16_bf16 v[64:79], v[88:91], v[104:107], v[64:79]
	s_waitcnt lgkmcnt(0)
	v_mfma_f32_32x32x16_bf16 v[64:79], v[92:95], v[108:111], v[64:79]
	s_waitcnt vmcnt(8)
	s_barrier
	s_add_i32 m0, s1, 0xc000
	s_nop 0
	global_load_lds_dwordx4 v[10:11], off sc1
	s_add_i32 m0, s1, 0xd000
	v_lshl_add_u64 v[10:11], v[10:11], 0, s[16:17]
	global_load_lds_dwordx4 v[12:13], off sc1
	s_add_i32 m0, s1, 0xe000
	v_lshl_add_u64 v[12:13], v[12:13], 0, s[16:17]
	global_load_lds_dwordx4 v[14:15], off
	s_add_i32 m0, s1, 0xf000
	v_lshl_add_u64 v[14:15], v[14:15], 0, s[16:17]
	global_load_lds_dwordx4 v[16:17], off
	v_lshl_add_u64 v[16:17], v[16:17], 0, s[16:17]
	ds_read_b128 v[80:83], v26 offset:0
	ds_read_b128 v[96:99], v30 offset:0
	ds_read_b128 v[84:87], v27 offset:0
	ds_read_b128 v[100:103], v31 offset:0
	ds_read_b128 v[88:91], v28 offset:0
	ds_read_b128 v[104:107], v32 offset:0
	ds_read_b128 v[92:95], v29 offset:0
	ds_read_b128 v[108:111], v33 offset:0
	s_waitcnt lgkmcnt(6)
	v_mfma_f32_32x32x16_bf16 v[64:79], v[80:83], v[96:99], v[64:79]
	s_waitcnt lgkmcnt(4)
	v_mfma_f32_32x32x16_bf16 v[64:79], v[84:87], v[100:103], v[64:79]
	s_waitcnt lgkmcnt(2)
	v_mfma_f32_32x32x16_bf16 v[64:79], v[88:91], v[104:107], v[64:79]
	s_waitcnt lgkmcnt(0)
	v_mfma_f32_32x32x16_bf16 v[64:79], v[92:95], v[108:111], v[64:79]
	s_waitcnt vmcnt(8)
	s_barrier
; DI void gemm_out(const Params& p, char* lds) {
;     ...
;             for (int ks = 0; ks < 2; ++ks) {
;                 bf16x8 fw[4], fx[3];
; #pragma unroll
;                 for (int ct = 0; ct < 4; ++ct) fw[ct] = *(const bf16x8*)(sb + swz(wn * 64 + ct * 16 + q, 4 * ks + g));
; #pragma unroll
;                 for (int tt = 0; tt < 3; ++tt) fx[tt] = *(const bf16x8*)(sa + swz(wm * 48 + tt * 16 + q, 4 * ks + g));
; #pragma unroll
;                 for (int ct = 0; ct < 4; ++ct)
; #pragma unroll
;                     for (int tt = 0; tt < 3; ++tt) acc[ct][tt] = __builtin_amdgcn_mfma_f32_16x16x32_bf16(fw[ct], fx[tt], acc[ct][tt], 0, 0, 0);
;             }
;             __syncthreads();
;         }
;     ...
; #pragma unroll
;         for (int tt = 0; tt < 3; ++tt) {
;             const int row = m0 + wm * 48 + tt * 16 + q;
;             const float* xr = row < NTP ? p.x_p + (size_t)row * DM : p.x_s + (size_t)(row - NTP) * DM;
;             float* o = p.out + (size_t)row * DM;
; #pragma unroll
;             for (int ct = 0; ct < 4; ++ct) { const int col = n0 + wn * 64 + ct * 16 + 4 * g; const float4 xv = xres[tt][ct];
;                 const f32x4 w = {xv.x + acc[ct][tt][0], xv.y + acc[ct][tt][1], xv.z + acc[ct][tt][2], xv.w + acc[ct][tt][3]}; __builtin_nontemporal_store(w, (f32x4*)(o + col)); }
;         }
	ds_read_b128 v[80:83], v26 offset:16384
	ds_read_b128 v[96:99], v30 offset:16384
	ds_read_b128 v[84:87], v27 offset:16384
	ds_read_b128 v[100:103], v31 offset:16384
	ds_read_b128 v[88:91], v28 offset:16384
	ds_read_b128 v[104:107], v32 offset:16384
	ds_read_b128 v[92:95], v29 offset:16384
	ds_read_b128 v[108:111], v33 offset:16384
	s_waitcnt lgkmcnt(6)
	v_mfma_f32_32x32x16_bf16 v[64:79], v[80:83], v[96:99], v[64:79]
	s_waitcnt lgkmcnt(4)
	v_mfma_f32_32x32x16_bf16 v[64:79], v[84:87], v[100:103], v[64:79]
	s_waitcnt lgkmcnt(2)
	v_mfma_f32_32x32x16_bf16 v[64:79], v[88:91], v[104:107], v[64:79]
	s_waitcnt lgkmcnt(0)
	v_mfma_f32_32x32x16_bf16 v[64:79], v[92:95], v[108:111], v[64:79]
	s_waitcnt vmcnt(4)
	s_barrier
	ds_read_b128 v[80:83], v26 offset:32768
	ds_read_b128 v[96:99], v30 offset:32768
	ds_read_b128 v[84:87], v27 offset:32768
	ds_read_b128 v[100:103], v31 offset:32768
	ds_read_b128 v[88:91], v28 offset:32768
	ds_read_b128 v[104:107], v32 offset:32768
	ds_read_b128 v[92:95], v29 offset:32768
	ds_read_b128 v[108:111], v33 offset:32768
	s_waitcnt lgkmcnt(6)
	v_mfma_f32_32x32x16_bf16 v[64:79], v[80:83], v[96:99], v[64:79]
	s_waitcnt lgkmcnt(4)
	v_mfma_f32_32x32x16_bf16 v[64:79], v[84:87], v[100:103], v[64:79]
	s_waitcnt lgkmcnt(2)
	v_mfma_f32_32x32x16_bf16 v[64:79], v[88:91], v[104:107], v[64:79]
	s_waitcnt lgkmcnt(0)
	v_mfma_f32_32x32x16_bf16 v[64:79], v[92:95], v[108:111], v[64:79]
	s_waitcnt vmcnt(0)
	s_barrier
	ds_read_b128 v[80:83], v26 offset:49152
	ds_read_b128 v[96:99], v30 offset:49152
	ds_read_b128 v[84:87], v27 offset:49152
	ds_read_b128 v[100:103], v31 offset:49152
	ds_read_b128 v[88:91], v28 offset:49152
	ds_read_b128 v[104:107], v32 offset:49152
	ds_read_b128 v[92:95], v29 offset:49152
	ds_read_b128 v[108:111], v33 offset:49152
	s_waitcnt lgkmcnt(6)
	v_mfma_f32_32x32x16_bf16 v[64:79], v[80:83], v[96:99], v[64:79]
	s_waitcnt lgkmcnt(4)
	v_mfma_f32_32x32x16_bf16 v[64:79], v[84:87], v[100:103], v[64:79]
	s_waitcnt lgkmcnt(2)
	v_mfma_f32_32x32x16_bf16 v[64:79], v[88:91], v[104:107], v[64:79]
	s_waitcnt lgkmcnt(0)
	v_mfma_f32_32x32x16_bf16 v[64:79], v[92:95], v[108:111], v[64:79]
	s_nop 15
	s_nop 7
	v_add_f32_e32 v64, v64, v40
	global_store_dword v35, v64, s[52:53] nt
	v_add_u32_e32 v35, 0x1000, v35
	v_add_f32_e32 v65, v65, v41
	global_store_dword v35, v65, s[52:53] nt
	v_add_u32_e32 v35, 0x1000, v35
	v_add_f32_e32 v66, v66, v42
	global_store_dword v35, v66, s[52:53] nt
	v_add_u32_e32 v35, 0x1000, v35
	v_add_f32_e32 v67, v67, v43
	global_store_dword v35, v67, s[52:53] nt
	v_add_u32_e32 v35, 0x5000, v35
	v_add_f32_e32 v68, v68, v44
	global_store_dword v35, v68, s[52:53] nt
	v_add_u32_e32 v35, 0x1000, v35
	v_add_f32_e32 v69, v69, v45
	global_store_dword v35, v69, s[52:53] nt
	v_add_u32_e32 v35, 0x1000, v35
	v_add_f32_e32 v70, v70, v46
	global_store_dword v35, v70, s[52:53] nt
	v_add_u32_e32 v35, 0x1000, v35
	v_add_f32_e32 v71, v71, v47
	global_store_dword v35, v71, s[52:53] nt
	v_add_u32_e32 v35, 0x5000, v35
	v_add_f32_e32 v72, v72, v48
	global_store_dword v35, v72, s[52:53] nt
	v_add_u32_e32 v35, 0x1000, v35
	v_add_f32_e32 v73, v73, v49
	global_store_dword v35, v73, s[52:53] nt
	v_add_u32_e32 v35, 0x1000, v35
	v_add_f32_e32 v74, v74, v50
	global_store_dword v35, v74, s[52:53] nt
	v_add_u32_e32 v35, 0x1000, v35
	v_add_f32_e32 v75, v75, v51
	global_store_dword v35, v75, s[52:53] nt
	v_add_u32_e32 v35, 0x5000, v35
	v_add_f32_e32 v76, v76, v52
	global_store_dword v35, v76, s[52:53] nt
	v_add_u32_e32 v35, 0x1000, v35
	v_add_f32_e32 v77, v77, v53
	global_store_dword v35, v77, s[52:53] nt
	v_add_u32_e32 v35, 0x1000, v35
	v_add_f32_e32 v78, v78, v54
	global_store_dword v35, v78, s[52:53] nt
	v_add_u32_e32 v35, 0x1000, v35
	v_add_f32_e32 v79, v79, v55
	global_store_dword v35, v79, s[52:53] nt
